# streaming loads of P0, conv and weight conversion marked non-temporal
# speedup vs baseline: 1.0255x; 1.0109x over previous
.LBB0_12:
	s_cmpk_gt_i32 s40, 0x5ff
	s_mov_b64 s[0:1], -1
	s_cbranch_scc0 .LBB0_26
	s_add_i32 s18, s40, 0xfffffa00
	s_cmpk_gt_u32 s18, 0x1ff
	s_cbranch_scc0 .LBB0_23
	s_cmpk_gt_u32 s18, 0xcff
	s_cbranch_scc0 .LBB0_16
	s_and_b32 s0, s25, 0x7fffffc0
	s_addk_i32 s0, 0xe600
	s_and_b32 s19, s13, 0x3e0
	v_or_b32_e32 v36, s0, v34
	s_lshl_b32 s6, s19, 2
	v_or_b32_e32 v4, 8, v36
	v_mov_b32_e32 v5, v37
	v_or_b32_e32 v10, 16, v36
	v_mov_b32_e32 v11, v37
	v_or_b32_e32 v12, 24, v36
	v_mov_b32_e32 v13, v37
	v_or_b32_e32 v18, 32, v36
	v_mov_b32_e32 v19, v37
	v_or_b32_e32 v20, 40, v36
	v_mov_b32_e32 v21, v37
	v_lshl_add_u64 v[30:31], v[46:47], 0, s[6:7]
	v_lshlrev_b64 v[2:3], 12, v[36:37]
	v_lshlrev_b64 v[4:5], 12, v[4:5]
	v_lshlrev_b64 v[10:11], 12, v[10:11]
	v_lshlrev_b64 v[12:13], 12, v[12:13]
	v_lshlrev_b64 v[18:19], 12, v[18:19]
	v_lshlrev_b64 v[20:21], 12, v[20:21]
	v_lshl_add_u64 v[2:3], v[30:31], 0, v[2:3]
	v_lshl_add_u64 v[6:7], v[30:31], 0, v[4:5]
	v_lshl_add_u64 v[10:11], v[30:31], 0, v[10:11]
	v_lshl_add_u64 v[14:15], v[30:31], 0, v[12:13]
	v_lshl_add_u64 v[18:19], v[30:31], 0, v[18:19]
	v_lshl_add_u64 v[22:23], v[30:31], 0, v[20:21]
	global_load_dwordx4 v[2:5], v[2:3], off nt
	s_nop 0
	global_load_dwordx4 v[6:9], v[6:7], off nt
	s_nop 0
	global_load_dwordx4 v[10:13], v[10:11], off nt
	s_nop 0
	global_load_dwordx4 v[14:17], v[14:15], off nt
	s_nop 0
	global_load_dwordx4 v[18:21], v[18:19], off nt
	s_nop 0
	global_load_dwordx4 v[22:25], v[22:23], off nt
	v_or_b32_e32 v26, 48, v36
	v_mov_b32_e32 v27, v37
	v_lshlrev_b64 v[26:27], 12, v[26:27]
	v_lshl_add_u64 v[26:27], v[30:31], 0, v[26:27]
	v_or_b32_e32 v36, 56, v36
	global_load_dwordx4 v[26:29], v[26:27], off nt
	v_lshlrev_b64 v[32:33], 12, v[36:37]
	v_lshl_add_u64 v[30:31], v[30:31], 0, v[32:33]
	global_load_dwordx4 v[30:33], v[30:31], off nt
	v_or_b32_e32 v36, s19, v34
	s_mov_b32 s1, s7
	v_mul_u32_u24_e32 v36, 0xb00, v36
	v_lshl_add_u64 v[54:55], s[0:1], 1, v[38:39]
	v_lshlrev_b32_e32 v36, 1, v36
	s_mov_b64 s[0:1], 0
	s_waitcnt vmcnt(7)
	ds_write2_b32 v67, v2, v3 offset1:1
	ds_write2_b32 v67, v4, v5 offset0:2 offset1:3
	s_waitcnt vmcnt(6)
	ds_write2_b32 v68, v6, v7 offset1:1
	ds_write2_b32 v69, v8, v9 offset1:1
	s_waitcnt vmcnt(5)
	ds_write2_b32 v70, v10, v11 offset1:1
	ds_write2_b32 v71, v12, v13 offset1:1
	s_waitcnt vmcnt(4)
	ds_write2_b32 v72, v14, v15 offset1:1
	ds_write2_b32 v73, v16, v17 offset1:1
	s_waitcnt vmcnt(3)
	ds_write2_b32 v74, v18, v19 offset1:1
	ds_write2_b32 v75, v20, v21 offset1:1
	s_waitcnt vmcnt(2)
	ds_write2_b32 v76, v22, v23 offset1:1
	ds_write2_b32 v77, v24, v25 offset1:1
	s_waitcnt vmcnt(1)
	ds_write2_b32 v78, v26, v27 offset1:1
	ds_write2_b32 v79, v28, v29 offset1:1
	s_waitcnt vmcnt(0)
	ds_write2_b32 v80, v30, v31 offset1:1
	ds_write2_b32 v81, v32, v33 offset1:1
	s_waitcnt lgkmcnt(0)
	ds_read2_b32 v[6:7], v61 offset0:33 offset1:41
	ds_read2_b32 v[8:9], v61 offset1:8
	ds_read2_b32 v[10:11], v61 offset0:66 offset1:74
	ds_read2_b32 v[12:13], v61 offset0:99 offset1:107
	ds_read2_b32 v[14:15], v61 offset0:132 offset1:140
	ds_read2_b32 v[16:17], v61 offset0:165 offset1:173
	ds_read2_b32 v[18:19], v61 offset0:198 offset1:206
	ds_read2_b32 v[20:21], v61 offset0:231 offset1:239
	s_waitcnt lgkmcnt(6)
	v_bfe_u32 v2, v8, 16, 1
	v_bfe_u32 v3, v6, 16, 1
	s_waitcnt lgkmcnt(5)
	v_bfe_u32 v4, v10, 16, 1
	s_waitcnt lgkmcnt(3)
	v_bfe_u32 v22, v14, 16, 1
	s_waitcnt lgkmcnt(1)
	v_bfe_u32 v24, v18, 16, 1
	v_bfe_u32 v5, v12, 16, 1
	v_bfe_u32 v23, v16, 16, 1
	s_waitcnt lgkmcnt(0)
	v_bfe_u32 v25, v20, 16, 1
	v_add3_u32 v2, v8, v2, s27
	v_add3_u32 v3, v6, v3, s27
	v_add3_u32 v4, v10, v4, s27
	v_add3_u32 v6, v14, v22, s27
	v_add3_u32 v10, v18, v24, s27
	v_add3_u32 v5, v12, v5, s27
	v_add3_u32 v8, v16, v23, s27
	v_add3_u32 v12, v20, v25, s27
	v_lshrrev_b32_e32 v2, 16, v2
	v_lshrrev_b32_e32 v4, 16, v4
	v_lshrrev_b32_e32 v6, 16, v6
	v_lshrrev_b32_e32 v10, 16, v10
	v_and_or_b32 v2, v3, s29, v2
	v_and_or_b32 v3, v5, s29, v4
	v_and_or_b32 v4, v8, s29, v6
	v_and_or_b32 v5, v12, s29, v10
	v_lshl_add_u64 v[22:23], v[54:55], 0, v[36:37]
	global_store_dwordx4 v[22:23], v[2:5], off
	v_bfe_u32 v6, v21, 16, 1
	v_add3_u32 v6, v21, v6, s27
	v_bfe_u32 v2, v9, 16, 1
	v_add3_u32 v2, v9, v2, s27
	v_bfe_u32 v3, v7, 16, 1
	v_lshrrev_b32_e32 v2, 16, v2
	v_add3_u32 v3, v7, v3, s27
	v_and_or_b32 v2, v3, s29, v2
	v_bfe_u32 v3, v11, 16, 1
	v_add3_u32 v3, v11, v3, s27
	v_bfe_u32 v4, v13, 16, 1
	v_lshrrev_b32_e32 v3, 16, v3
	v_add3_u32 v4, v13, v4, s27
	v_and_or_b32 v3, v4, s29, v3
	v_bfe_u32 v4, v15, 16, 1
	v_add3_u32 v4, v15, v4, s27
	v_bfe_u32 v5, v17, 16, 1
	v_lshrrev_b32_e32 v4, 16, v4
	v_add3_u32 v5, v17, v5, s27
	v_and_or_b32 v4, v5, s29, v4
	v_bfe_u32 v5, v19, 16, 1
	v_add3_u32 v5, v19, v5, s27
	v_lshrrev_b32_e32 v5, 16, v5
	v_and_or_b32 v5, v6, s29, v5
	v_or_b32_e32 v6, s19, v58
	v_mul_u32_u24_e32 v8, 0xb00, v6
	v_lshlrev_b32_e32 v36, 1, v8
	ds_read2_b32 v[6:7], v61 offset0:16 offset1:24
	v_lshl_add_u64 v[8:9], v[54:55], 0, v[36:37]
	global_store_dwordx4 v[8:9], v[2:5], off
	ds_read2_b32 v[8:9], v61 offset0:49 offset1:57
	ds_read2_b32 v[10:11], v61 offset0:82 offset1:90
	ds_read2_b32 v[12:13], v61 offset0:115 offset1:123
	s_waitcnt lgkmcnt(3)
	v_bfe_u32 v2, v6, 16, 1
	v_add3_u32 v2, v6, v2, s27
	s_waitcnt lgkmcnt(2)
	v_bfe_u32 v3, v8, 16, 1
	ds_read2_b32 v[14:15], v61 offset0:148 offset1:156
	v_lshrrev_b32_e32 v2, 16, v2
	v_add3_u32 v3, v8, v3, s27
	ds_read2_b32 v[16:17], v61 offset0:181 offset1:189
	v_and_or_b32 v2, v3, s29, v2
	s_waitcnt lgkmcnt(3)
	v_bfe_u32 v3, v10, 16, 1
	v_add3_u32 v3, v10, v3, s27
	s_waitcnt lgkmcnt(2)
	v_bfe_u32 v4, v12, 16, 1
	ds_read2_b32 v[18:19], v61 offset0:214 offset1:222
	v_lshrrev_b32_e32 v3, 16, v3
	v_add3_u32 v4, v12, v4, s27
	ds_read2_b32 v[20:21], v61 offset0:247 offset1:255
	v_and_or_b32 v3, v4, s29, v3
	s_waitcnt lgkmcnt(3)
	v_bfe_u32 v4, v14, 16, 1
	v_add3_u32 v4, v14, v4, s27
	s_waitcnt lgkmcnt(2)
	v_bfe_u32 v5, v16, 16, 1
	v_lshrrev_b32_e32 v4, 16, v4
	v_add3_u32 v5, v16, v5, s27
	v_and_or_b32 v4, v5, s29, v4
	s_waitcnt lgkmcnt(1)
	v_bfe_u32 v5, v18, 16, 1
	v_add3_u32 v5, v18, v5, s27
	s_waitcnt lgkmcnt(0)
	v_bfe_u32 v6, v20, 16, 1
	v_lshrrev_b32_e32 v5, 16, v5
	v_add3_u32 v6, v20, v6, s27
	v_and_or_b32 v5, v6, s29, v5
	v_or_b32_e32 v6, s19, v59
	v_mul_u32_u24_e32 v6, 0xb00, v6
	v_lshlrev_b32_e32 v36, 1, v6
	v_lshl_add_u64 v[22:23], v[54:55], 0, v[36:37]
	global_store_dwordx4 v[22:23], v[2:5], off
	v_bfe_u32 v6, v21, 16, 1
	v_add3_u32 v6, v21, v6, s27
	v_bfe_u32 v2, v7, 16, 1
	v_add3_u32 v2, v7, v2, s27
	v_bfe_u32 v3, v9, 16, 1
	v_lshrrev_b32_e32 v2, 16, v2
	v_add3_u32 v3, v9, v3, s27
	v_and_or_b32 v2, v3, s29, v2
	v_bfe_u32 v3, v11, 16, 1
	v_add3_u32 v3, v11, v3, s27
	v_bfe_u32 v4, v13, 16, 1
	v_lshrrev_b32_e32 v3, 16, v3
	v_add3_u32 v4, v13, v4, s27
	v_and_or_b32 v3, v4, s29, v3
	v_bfe_u32 v4, v15, 16, 1
	v_add3_u32 v4, v15, v4, s27
	v_bfe_u32 v5, v17, 16, 1
	v_lshrrev_b32_e32 v4, 16, v4
	v_add3_u32 v5, v17, v5, s27
	v_and_or_b32 v4, v5, s29, v4
	v_bfe_u32 v5, v19, 16, 1
	v_add3_u32 v5, v19, v5, s27
	v_lshrrev_b32_e32 v5, 16, v5
	v_and_or_b32 v5, v6, s29, v5
	v_or_b32_e32 v6, s19, v60
	v_mul_u32_u24_e32 v6, 0xb00, v6
	v_lshlrev_b32_e32 v36, 1, v6
	v_lshl_add_u64 v[6:7], v[54:55], 0, v[36:37]
	global_store_dwordx4 v[6:7], v[2:5], off
	s_waitcnt lgkmcnt(0)
.LBB0_16:
	s_andn2_b64 vcc, exec, s[0:1]
	s_cbranch_vccnz .LBB0_22
	s_add_i32 s18, s18, 0xfe00
	s_and_b32 s0, s18, 0xffff
	s_mul_i32 s0, s0, 0xba2f
	s_lshr_b32 s0, s0, 23
	s_mul_i32 s1, s0, 0xb0
	s_sub_i32 s1, s18, s1
	s_lshl_b32 s18, s0, 6
	s_and_b32 s19, s1, 0xffff
	v_or_b32_e32 v22, s18, v34
	s_lshl_b32 s6, s19, 7
	v_mul_u32_u24_e32 v6, 0x1600, v22
	v_lshl_add_u64 v[2:3], v[48:49], 0, s[6:7]
	v_lshlrev_b32_e32 v36, 2, v6
	v_lshl_add_u64 v[30:31], v[2:3], 0, v[36:37]
	v_add_co_u32_e32 v6, vcc, s31, v30
	v_mad_u64_u32 v[4:5], s[0:1], v22, s30, v[2:3]
	s_nop 0
	v_addc_co_u32_e32 v7, vcc, 0, v31, vcc
	v_add_co_u32_e32 v10, vcc, s33, v30
	v_lshlrev_b32_e32 v22, 2, v22
	s_nop 0
	v_addc_co_u32_e32 v11, vcc, 0, v31, vcc
	v_add_co_u32_e32 v14, vcc, s34, v30
	global_load_dwordx4 v[2:5], v[4:5], off nt
	s_nop 0
	global_load_dwordx4 v[6:9], v[6:7], off nt
	v_addc_co_u32_e32 v15, vcc, 0, v31, vcc
	global_load_dwordx4 v[10:13], v[10:11], off nt
	s_nop 0
	global_load_dwordx4 v[14:17], v[14:15], off nt
	v_add_co_u32_e32 v18, vcc, s35, v30
	global_load_dword v36, v22, s[14:15]
	v_or_b32_e32 v22, s18, v58
	v_addc_co_u32_e32 v19, vcc, 0, v31, vcc
	v_lshlrev_b32_e32 v22, 2, v22
	v_or_b32_e32 v23, s18, v59
	global_load_dwordx4 v[18:21], v[18:19], off nt
	v_lshlrev_b32_e32 v23, 2, v23
	global_load_dword v54, v22, s[14:15]
	global_load_dword v56, v23, s[14:15]
	v_or_b32_e32 v22, s18, v60
	v_lshlrev_b32_e32 v22, 2, v22
	v_or_b32_e32 v23, s18, v62
	v_lshlrev_b32_e32 v23, 2, v23
	global_load_dword v82, v22, s[14:15]
	global_load_dword v84, v23, s[14:15]
	v_add_co_u32_e32 v22, vcc, s36, v30
	v_or_b32_e32 v28, s18, v64
	s_nop 0
	v_addc_co_u32_e32 v23, vcc, 0, v31, vcc
	v_add_co_u32_e32 v26, vcc, s37, v30
	global_load_dwordx4 v[22:25], v[22:23], off nt
	s_nop 0
	v_addc_co_u32_e32 v27, vcc, 0, v31, vcc
	v_lshlrev_b32_e32 v28, 2, v28
	v_or_b32_e32 v32, s18, v65
	global_load_dword v86, v28, s[14:15]
	s_nop 0
	global_load_dwordx4 v[26:29], v[26:27], off nt
	v_lshlrev_b32_e32 v32, 2, v32
	global_load_dword v88, v32, s[14:15]
	v_add_co_u32_e32 v30, vcc, s38, v30
	v_or_b32_e32 v32, s18, v66
	s_nop 0
	v_addc_co_u32_e32 v31, vcc, 0, v31, vcc
	v_lshlrev_b32_e32 v32, 2, v32
	global_load_dword v90, v32, s[14:15]
	s_nop 0
	global_load_dwordx4 v[30:33], v[30:31], off nt
	s_lshl_b32 s6, s19, 5
	s_lshl_b32 s20, s19, 6
	s_cmpk_gt_u32 s19, 0x57
	s_mov_b64 s[0:1], -1
	s_waitcnt vmcnt(11)
	v_pk_mul_f32 v[2:3], v[2:3], v[36:37] op_sel_hi:[1,0]
	v_pk_mul_f32 v[4:5], v[4:5], v[36:37] op_sel_hi:[1,0]
	ds_write2_b32 v67, v2, v3 offset1:1
	ds_write2_b32 v67, v4, v5 offset0:2 offset1:3
	s_waitcnt vmcnt(9)
	v_pk_mul_f32 v[2:3], v[6:7], v[54:55] op_sel_hi:[1,0]
	v_pk_mul_f32 v[4:5], v[8:9], v[54:55] op_sel_hi:[1,0]
	s_waitcnt vmcnt(8)
	v_pk_mul_f32 v[6:7], v[10:11], v[56:57] op_sel_hi:[1,0]
	v_pk_mul_f32 v[8:9], v[12:13], v[56:57] op_sel_hi:[1,0]
	s_waitcnt vmcnt(7)
	v_pk_mul_f32 v[10:11], v[14:15], v[82:83] op_sel_hi:[1,0]
	v_pk_mul_f32 v[12:13], v[16:17], v[82:83] op_sel_hi:[1,0]
	ds_write2_b32 v68, v2, v3 offset1:1
	ds_write2_b32 v69, v4, v5 offset1:1
	ds_write2_b32 v70, v6, v7 offset1:1
	ds_write2_b32 v71, v8, v9 offset1:1
	ds_write2_b32 v72, v10, v11 offset1:1
	ds_write2_b32 v73, v12, v13 offset1:1
	v_add_u32_e32 v4, v57, v63
	s_waitcnt vmcnt(6)
	v_pk_mul_f32 v[2:3], v[20:21], v[84:85] op_sel_hi:[1,0]
	ds_write2_b32 v4, v2, v3 offset0:2 offset1:3
	v_add_u32_e32 v5, 0x420, v4
	v_pk_mul_f32 v[14:15], v[18:19], v[84:85] op_sel_hi:[1,0]
	ds_write2_b32 v4, v14, v15 offset1:1
	s_waitcnt vmcnt(4)
	v_pk_mul_f32 v[2:3], v[22:23], v[86:87] op_sel_hi:[1,0]
	ds_write2_b32 v5, v2, v3 offset1:1
	v_pk_mul_f32 v[2:3], v[24:25], v[86:87] op_sel_hi:[1,0]
	v_add_u32_e32 v5, 0x428, v4
	ds_write2_b32 v5, v2, v3 offset1:1
	s_waitcnt vmcnt(2)
	v_pk_mul_f32 v[2:3], v[26:27], v[88:89] op_sel_hi:[1,0]
	v_add_u32_e32 v5, 0x840, v4
	ds_write2_b32 v5, v2, v3 offset1:1
	v_pk_mul_f32 v[2:3], v[28:29], v[88:89] op_sel_hi:[1,0]
	v_add_u32_e32 v5, 0x848, v4
	ds_write2_b32 v5, v2, v3 offset1:1
	s_waitcnt vmcnt(0)
	v_pk_mul_f32 v[2:3], v[30:31], v[90:91] op_sel_hi:[1,0]
	v_add_u32_e32 v5, 0xc60, v4
	ds_write2_b32 v5, v2, v3 offset1:1
	v_pk_mul_f32 v[2:3], v[32:33], v[90:91] op_sel_hi:[1,0]
	v_add_u32_e32 v4, 0xc68, v4
	ds_write2_b32 v4, v2, v3 offset1:1
	s_waitcnt lgkmcnt(0)
	s_cbranch_scc0 .LBB0_19
	s_add_i32 s0, s20, 0x7fffea00
	s_and_b32 s0, s0, 0x7fffff00
	s_and_b32 s1, s6, 0x60
	s_or_b32 s0, s1, s0
	s_or_b32 s19, s0, 0x80
	s_mov_b64 s[0:1], 0

.LBB0_23:
	s_andn2_b64 vcc, exec, s[0:1]
	s_cbranch_vccnz .LBB0_25
	s_and_b32 s1, s25, 0x3c0
	s_and_b32 s0, s13, 0x3e0
	v_or_b32_e32 v4, s1, v34
	s_lshl_b32 s6, s0, 2
	v_lshl_add_u64 v[2:3], v[50:51], 0, s[6:7]
	v_lshlrev_b32_e32 v36, 12, v4
	v_lshl_add_u64 v[30:31], v[2:3], 0, v[36:37]
	v_add_co_u32_e32 v6, vcc, 0x8000, v30
	v_or_b32_e32 v36, s0, v34
	s_nop 0
	v_addc_co_u32_e32 v7, vcc, 0, v31, vcc
	v_add_co_u32_e32 v10, vcc, 0x10000, v30
	global_load_dwordx4 v[2:5], v[30:31], off nt
	s_nop 0
	global_load_dwordx4 v[6:9], v[6:7], off nt
	v_addc_co_u32_e32 v11, vcc, 0, v31, vcc
	v_add_co_u32_e32 v14, vcc, 0x18000, v30
	s_lshl_b32 s6, s1, 1
	s_nop 0
	v_addc_co_u32_e32 v15, vcc, 0, v31, vcc
	v_add_co_u32_e32 v18, vcc, 0x20000, v30
	global_load_dwordx4 v[10:13], v[10:11], off nt
	s_nop 0
	global_load_dwordx4 v[14:17], v[14:15], off nt
	v_addc_co_u32_e32 v19, vcc, 0, v31, vcc
	v_add_co_u32_e32 v22, vcc, 0x28000, v30
	v_lshl_add_u64 v[54:55], v[42:43], 0, s[6:7]
	s_nop 0
	v_addc_co_u32_e32 v23, vcc, 0, v31, vcc
	global_load_dwordx4 v[18:21], v[18:19], off nt
	s_nop 0
	global_load_dwordx4 v[22:25], v[22:23], off nt
	v_add_co_u32_e32 v26, vcc, 0x30000, v30
	v_lshlrev_b32_e32 v36, 11, v36
	s_nop 0
	v_addc_co_u32_e32 v27, vcc, 0, v31, vcc
	global_load_dwordx4 v[26:29], v[26:27], off nt
	v_add_co_u32_e32 v30, vcc, 0x38000, v30
	s_nop 1
	v_addc_co_u32_e32 v31, vcc, 0, v31, vcc
	global_load_dwordx4 v[30:33], v[30:31], off nt
	s_waitcnt vmcnt(7)
	ds_write2_b32 v67, v2, v3 offset1:1
	ds_write2_b32 v67, v4, v5 offset0:2 offset1:3
	s_waitcnt vmcnt(6)
	ds_write2_b32 v68, v6, v7 offset1:1
	ds_write2_b32 v69, v8, v9 offset1:1
	s_waitcnt vmcnt(5)
	ds_write2_b32 v70, v10, v11 offset1:1
	ds_write2_b32 v71, v12, v13 offset1:1
	s_waitcnt vmcnt(4)
	ds_write2_b32 v72, v14, v15 offset1:1
	ds_write2_b32 v73, v16, v17 offset1:1
	s_waitcnt vmcnt(3)
	ds_write2_b32 v74, v18, v19 offset1:1
	ds_write2_b32 v75, v20, v21 offset1:1
	s_waitcnt vmcnt(2)
	ds_write2_b32 v76, v22, v23 offset1:1
	ds_write2_b32 v77, v24, v25 offset1:1
	s_waitcnt vmcnt(1)
	ds_write2_b32 v78, v26, v27 offset1:1
	ds_write2_b32 v79, v28, v29 offset1:1
	s_waitcnt vmcnt(0)
	ds_write2_b32 v80, v30, v31 offset1:1
	ds_write2_b32 v81, v32, v33 offset1:1
	s_waitcnt lgkmcnt(0)
	ds_read2_b32 v[6:7], v61 offset0:33 offset1:41
	ds_read2_b32 v[8:9], v61 offset1:8
	ds_read2_b32 v[10:11], v61 offset0:66 offset1:74
	ds_read2_b32 v[12:13], v61 offset0:99 offset1:107
	ds_read2_b32 v[14:15], v61 offset0:132 offset1:140
	ds_read2_b32 v[16:17], v61 offset0:165 offset1:173
	ds_read2_b32 v[18:19], v61 offset0:198 offset1:206
	ds_read2_b32 v[20:21], v61 offset0:231 offset1:239
	s_waitcnt lgkmcnt(6)
	v_bfe_u32 v2, v8, 16, 1
	v_bfe_u32 v3, v6, 16, 1
	s_waitcnt lgkmcnt(5)
	v_bfe_u32 v4, v10, 16, 1
	s_waitcnt lgkmcnt(3)
	v_bfe_u32 v22, v14, 16, 1
	s_waitcnt lgkmcnt(1)
	v_bfe_u32 v24, v18, 16, 1
	v_bfe_u32 v5, v12, 16, 1
	v_bfe_u32 v23, v16, 16, 1
	s_waitcnt lgkmcnt(0)
	v_bfe_u32 v25, v20, 16, 1
	v_add3_u32 v2, v8, v2, s27
	v_add3_u32 v3, v6, v3, s27
	v_add3_u32 v4, v10, v4, s27
	v_add3_u32 v6, v14, v22, s27
	v_add3_u32 v10, v18, v24, s27
	v_add3_u32 v5, v12, v5, s27
	v_add3_u32 v8, v16, v23, s27
	v_add3_u32 v12, v20, v25, s27
	v_lshrrev_b32_e32 v2, 16, v2
	v_lshrrev_b32_e32 v4, 16, v4
	v_lshrrev_b32_e32 v6, 16, v6
	v_lshrrev_b32_e32 v10, 16, v10
	v_and_or_b32 v2, v3, s29, v2
	v_and_or_b32 v3, v5, s29, v4
	v_and_or_b32 v4, v8, s29, v6
	v_and_or_b32 v5, v12, s29, v10
	v_lshl_add_u64 v[22:23], v[54:55], 0, v[36:37]
	global_store_dwordx4 v[22:23], v[2:5], off
	v_bfe_u32 v6, v21, 16, 1
	v_or_b32_e32 v8, s0, v58
	v_bfe_u32 v2, v9, 16, 1
	v_add3_u32 v2, v9, v2, s27
	v_bfe_u32 v3, v7, 16, 1
	v_lshrrev_b32_e32 v2, 16, v2
	v_add3_u32 v3, v7, v3, s27
	v_and_or_b32 v2, v3, s29, v2
	v_bfe_u32 v3, v11, 16, 1
	v_add3_u32 v3, v11, v3, s27
	v_bfe_u32 v4, v13, 16, 1
	v_lshrrev_b32_e32 v3, 16, v3
	v_add3_u32 v4, v13, v4, s27
	v_and_or_b32 v3, v4, s29, v3
	v_bfe_u32 v4, v15, 16, 1
	v_add3_u32 v4, v15, v4, s27
	v_bfe_u32 v5, v17, 16, 1
	v_lshrrev_b32_e32 v4, 16, v4
	v_add3_u32 v5, v17, v5, s27
	v_and_or_b32 v4, v5, s29, v4
	v_bfe_u32 v5, v19, 16, 1
	v_add3_u32 v5, v19, v5, s27
	v_lshrrev_b32_e32 v5, 16, v5
	v_add3_u32 v6, v21, v6, s27
	v_lshlrev_b32_e32 v36, 11, v8
	v_and_or_b32 v5, v6, s29, v5
	ds_read2_b32 v[6:7], v61 offset0:16 offset1:24
	v_lshl_add_u64 v[8:9], v[54:55], 0, v[36:37]
	global_store_dwordx4 v[8:9], v[2:5], off
	ds_read2_b32 v[8:9], v61 offset0:49 offset1:57
	ds_read2_b32 v[10:11], v61 offset0:82 offset1:90
	ds_read2_b32 v[12:13], v61 offset0:115 offset1:123
	s_waitcnt lgkmcnt(3)
	v_bfe_u32 v2, v6, 16, 1
	v_add3_u32 v2, v6, v2, s27
	s_waitcnt lgkmcnt(2)
	v_bfe_u32 v3, v8, 16, 1
	ds_read2_b32 v[14:15], v61 offset0:148 offset1:156
	v_lshrrev_b32_e32 v2, 16, v2
	v_add3_u32 v3, v8, v3, s27
	ds_read2_b32 v[16:17], v61 offset0:181 offset1:189
	v_and_or_b32 v2, v3, s29, v2
	s_waitcnt lgkmcnt(3)
	v_bfe_u32 v3, v10, 16, 1
	v_add3_u32 v3, v10, v3, s27
	s_waitcnt lgkmcnt(2)
	v_bfe_u32 v4, v12, 16, 1
	ds_read2_b32 v[18:19], v61 offset0:214 offset1:222
	v_lshrrev_b32_e32 v3, 16, v3
	v_add3_u32 v4, v12, v4, s27
	ds_read2_b32 v[20:21], v61 offset0:247 offset1:255
	v_and_or_b32 v3, v4, s29, v3
	s_waitcnt lgkmcnt(3)
	v_bfe_u32 v4, v14, 16, 1
	v_add3_u32 v4, v14, v4, s27
	s_waitcnt lgkmcnt(2)
	v_bfe_u32 v5, v16, 16, 1
	v_lshrrev_b32_e32 v4, 16, v4
	v_add3_u32 v5, v16, v5, s27
	v_and_or_b32 v4, v5, s29, v4
	s_waitcnt lgkmcnt(1)
	v_bfe_u32 v5, v18, 16, 1
	v_add3_u32 v5, v18, v5, s27
	s_waitcnt lgkmcnt(0)
	v_bfe_u32 v6, v20, 16, 1
	v_lshrrev_b32_e32 v5, 16, v5
	v_add3_u32 v6, v20, v6, s27
	v_and_or_b32 v5, v6, s29, v5
	v_or_b32_e32 v6, s0, v59
	v_lshlrev_b32_e32 v36, 11, v6
	v_lshl_add_u64 v[22:23], v[54:55], 0, v[36:37]
	global_store_dwordx4 v[22:23], v[2:5], off
	v_bfe_u32 v6, v21, 16, 1
	v_add3_u32 v6, v21, v6, s27
	v_bfe_u32 v2, v7, 16, 1
	v_add3_u32 v2, v7, v2, s27
	v_bfe_u32 v3, v9, 16, 1
	v_lshrrev_b32_e32 v2, 16, v2
	v_add3_u32 v3, v9, v3, s27
	v_and_or_b32 v2, v3, s29, v2
	v_bfe_u32 v3, v11, 16, 1
	v_add3_u32 v3, v11, v3, s27
	v_bfe_u32 v4, v13, 16, 1
	v_lshrrev_b32_e32 v3, 16, v3
	v_add3_u32 v4, v13, v4, s27
	v_and_or_b32 v3, v4, s29, v3
	v_bfe_u32 v4, v15, 16, 1
	v_add3_u32 v4, v15, v4, s27
	v_bfe_u32 v5, v17, 16, 1
	v_lshrrev_b32_e32 v4, 16, v4
	v_add3_u32 v5, v17, v5, s27
	v_and_or_b32 v4, v5, s29, v4
	v_bfe_u32 v5, v19, 16, 1
	v_add3_u32 v5, v19, v5, s27
	v_lshrrev_b32_e32 v5, 16, v5
	v_and_or_b32 v5, v6, s29, v5
	v_or_b32_e32 v6, s0, v60
	v_lshlrev_b32_e32 v36, 11, v6
	v_lshl_add_u64 v[6:7], v[54:55], 0, v[36:37]
	global_store_dwordx4 v[6:7], v[2:5], off
	s_waitcnt lgkmcnt(0)

.LBB0_26:
	s_andn2_b64 vcc, exec, s[0:1]
	s_cbranch_vccnz .LBB0_11
	s_mul_hi_i32 s0, s40, 0x2aaaaaab
	s_lshr_b32 s1, s0, 31
	s_ashr_i32 s6, s0, 4
	s_add_i32 s6, s6, s1
	s_mul_i32 s0, s6, 0xfffff400
	s_lshl_b32 s20, s6, 6
	s_add_i32 s18, s13, s0
	v_or_b32_e32 v54, s20, v34
	s_ashr_i32 s19, s18, 31
	v_lshl_add_u64 v[2:3], s[18:19], 2, v[52:53]
	v_or_b32_e32 v6, 8, v54
	v_mad_i64_i32 v[4:5], s[0:1], v54, s39, v[2:3]
	v_mad_i64_i32 v[6:7], s[0:1], v6, s39, v[2:3]
	global_load_dwordx4 v[30:33], v[4:5], off nt
	global_load_dwordx4 v[26:29], v[6:7], off nt
	v_or_b32_e32 v4, 16, v54
	v_or_b32_e32 v6, 24, v54
	v_mad_i64_i32 v[4:5], s[0:1], v4, s39, v[2:3]
	v_mad_i64_i32 v[6:7], s[0:1], v6, s39, v[2:3]
	global_load_dwordx4 v[22:25], v[4:5], off nt
	global_load_dwordx4 v[18:21], v[6:7], off nt
	v_or_b32_e32 v4, 32, v54
	v_or_b32_e32 v6, 40, v54
	v_mad_i64_i32 v[4:5], s[0:1], v4, s39, v[2:3]
	v_mad_i64_i32 v[6:7], s[0:1], v6, s39, v[2:3]
	global_load_dwordx4 v[14:17], v[4:5], off nt
	global_load_dwordx4 v[10:13], v[6:7], off nt
	v_or_b32_e32 v4, 48, v54
	v_or_b32_e32 v6, 56, v54
	v_mad_i64_i32 v[4:5], s[0:1], v4, s39, v[2:3]
	v_mad_i64_i32 v[2:3], s[0:1], v6, s39, v[2:3]
	global_load_dwordx4 v[6:9], v[4:5], off nt
	s_nop 0
	global_load_dwordx4 v[2:5], v[2:3], off nt
	v_cndmask_b32_e64 v55, 0, 1, s[16:17]
	v_mov_b32_e32 v36, 1.0
	v_cmp_ne_u32_e64 s[0:1], 1, v55
	s_andn2_b64 vcc, exec, s[16:17]
	v_mov_b32_e32 v56, 1.0
	s_cbranch_vccnz .LBB0_29
	v_readlane_b32 s44, v250, 1
	v_ashrrev_i32_e32 v55, 31, v54
	v_readlane_b32 s46, v250, 3
	v_readlane_b32 s47, v250, 4
	s_ashr_i32 s21, s20, 31
	v_lshl_add_u64 v[82:83], s[20:21], 0, v[34:35]
	v_lshl_add_u64 v[54:55], v[54:55], 2, s[46:47]
	global_load_dword v54, v[54:55], off
	v_lshl_add_u64 v[82:83], v[82:83], 2, s[46:47]
	global_load_dword v56, v[82:83], off offset:32
	v_readlane_b32 s45, v250, 2
	v_readlane_b32 s48, v250, 5
	v_readlane_b32 s49, v250, 6
	v_readlane_b32 s50, v250, 7
	v_readlane_b32 s51, v250, 8
	v_readlane_b32 s52, v250, 9
	v_readlane_b32 s53, v250, 10
	v_readlane_b32 s54, v250, 11
	v_readlane_b32 s55, v250, 12
	v_readlane_b32 s56, v250, 13
	v_readlane_b32 s57, v250, 14
	v_readlane_b32 s58, v250, 15
	v_readlane_b32 s59, v250, 16
	s_waitcnt vmcnt(1)
	v_pk_mul_f32 v[30:31], v[30:31], v[54:55] op_sel_hi:[1,0]
	v_pk_mul_f32 v[32:33], v[32:33], v[54:55] op_sel_hi:[1,0]

.LBB0_42:
	v_lshl_add_u64 v[10:11], s[24:25], 0, v[2:3]
	v_lshl_add_u64 v[12:13], s[20:21], 0, v[2:3]
	global_load_dwordx4 v[22:25], v[10:11], off nt
	global_load_dwordx4 v[26:29], v[12:13], off nt
	global_load_dwordx4 v[30:33], v[10:11], off offset:1024 nt
	global_load_dwordx4 v[34:37], v[12:13], off offset:1024 nt
	global_load_dwordx4 v[38:41], v[10:11], off offset:2048 nt
	global_load_dwordx4 v[42:45], v[12:13], off offset:2048 nt
	global_load_dwordx4 v[46:49], v[10:11], off offset:3072 nt
	s_nop 0
	global_load_dwordx4 v[10:13], v[12:13], off offset:3072 nt
	s_add_i32 s12, s12, s14
	s_add_u32 s20, s20, s22
	s_addc_u32 s21, s21, s23
	s_add_u32 s24, s24, s22
	v_lshl_add_u64 v[8:9], v[4:5], 0, s[16:17]
	s_addc_u32 s25, s25, s23
	v_lshl_add_u64 v[6:7], v[4:5], 0, s[26:27]
	v_lshl_add_u64 v[4:5], v[4:5], 0, s[18:19]
	s_cmpk_gt_i32 s12, 0x7fff
	s_waitcnt vmcnt(7)
	v_mul_f32_e32 v50, v23, v23
	v_mul_f32_e32 v51, v25, v25
	s_waitcnt vmcnt(6)
	v_mul_f32_e32 v52, v27, v27
	v_mul_f32_e32 v53, v29, v29
	s_waitcnt vmcnt(5)
	v_mul_f32_e32 v54, v31, v31
	v_mul_f32_e32 v55, v33, v33
	s_waitcnt vmcnt(4)
	v_mul_f32_e32 v56, v35, v35
	v_mul_f32_e32 v57, v37, v37
	s_waitcnt vmcnt(3)
	v_mul_f32_e32 v58, v39, v39
	v_mul_f32_e32 v59, v41, v41
	v_fmac_f32_e32 v50, v22, v22
	v_fmac_f32_e32 v51, v24, v24
	v_fmac_f32_e32 v52, v26, v26
	v_fmac_f32_e32 v53, v28, v28
	v_fmac_f32_e32 v54, v30, v30
	v_fmac_f32_e32 v55, v32, v32
	s_waitcnt vmcnt(2)
	v_mul_f32_e32 v60, v43, v43
	v_mul_f32_e32 v61, v45, v45
	s_waitcnt vmcnt(1)
	v_mul_f32_e32 v62, v47, v47
	v_mul_f32_e32 v63, v49, v49
	v_fmac_f32_e32 v56, v34, v34
	v_fmac_f32_e32 v57, v36, v36
	v_fmac_f32_e32 v58, v38, v38
	v_fmac_f32_e32 v59, v40, v40
	v_add_f32_e32 v50, v50, v51
	v_add_f32_e32 v51, v52, v53
	v_add_f32_e32 v52, v54, v55
	s_waitcnt vmcnt(0)
	v_mul_f32_e32 v64, v11, v11
	v_mul_f32_e32 v65, v13, v13
	v_fmac_f32_e32 v60, v42, v42
	v_fmac_f32_e32 v61, v44, v44
	v_fmac_f32_e32 v62, v46, v46
	v_fmac_f32_e32 v63, v48, v48
	v_add_f32_e32 v53, v56, v57
	v_add_f32_e32 v54, v58, v59
	v_add_f32_e32 v50, v50, v52
	v_fmac_f32_e32 v64, v10, v10
	v_fmac_f32_e32 v65, v12, v12
	v_add_f32_e32 v55, v60, v61
	v_add_f32_e32 v56, v62, v63
	v_add_f32_e32 v51, v51, v53
	v_add_f32_e32 v50, v50, v54
	v_add_f32_e32 v57, v64, v65
	v_add_f32_e32 v51, v51, v55
	v_add_f32_e32 v50, v50, v56
	v_add_f32_e32 v51, v51, v57
	ds_bpermute_b32 v52, v15, v50
	ds_bpermute_b32 v53, v15, v51
	s_waitcnt lgkmcnt(1)
	v_add_f32_e32 v50, v50, v52
	s_waitcnt lgkmcnt(0)
	v_add_f32_e32 v51, v51, v53
	ds_bpermute_b32 v52, v16, v50
	ds_bpermute_b32 v53, v16, v51
	s_waitcnt lgkmcnt(1)
	v_add_f32_e32 v50, v50, v52
	s_waitcnt lgkmcnt(0)
	v_add_f32_e32 v51, v51, v53
	ds_bpermute_b32 v52, v17, v50
	ds_bpermute_b32 v53, v17, v51
	s_waitcnt lgkmcnt(1)
	v_add_f32_e32 v50, v50, v52
	s_waitcnt lgkmcnt(0)
	v_add_f32_e32 v51, v51, v53
	ds_bpermute_b32 v52, v18, v50
	ds_bpermute_b32 v53, v18, v51
	s_waitcnt lgkmcnt(1)
	v_add_f32_e32 v50, v50, v52
	s_waitcnt lgkmcnt(0)
	v_add_f32_e32 v51, v51, v53
	ds_bpermute_b32 v52, v19, v50
	ds_bpermute_b32 v53, v19, v51
	s_waitcnt lgkmcnt(1)
	v_add_f32_e32 v50, v50, v52
	s_waitcnt lgkmcnt(0)
	v_add_f32_e32 v51, v51, v53
	ds_bpermute_b32 v52, v20, v50
	ds_bpermute_b32 v53, v20, v51
	s_waitcnt lgkmcnt(1)
	v_add_f32_e32 v50, v50, v52
	s_waitcnt lgkmcnt(0)
	v_add_f32_e32 v51, v51, v53
	v_fmamk_f32 v50, v50, 0x3a800000, v1
	v_fmamk_f32 v51, v51, 0x3a800000, v1
	v_mul_f32_e32 v52, 0x4f800000, v50
	v_cmp_gt_f32_e64 s[0:1], s13, v50
	v_mul_f32_e32 v53, 0x4f800000, v51
	v_cmp_gt_f32_e32 vcc, s13, v51
	v_cndmask_b32_e64 v50, v50, v52, s[0:1]
	v_sqrt_f32_e32 v52, v50
	v_cndmask_b32_e32 v51, v51, v53, vcc
	v_sqrt_f32_e32 v53, v51
	v_add_u32_e32 v54, -1, v52
	v_add_u32_e32 v55, 1, v52
	v_add_u32_e32 v56, -1, v53
	v_fma_f32 v58, -v54, v52, v50
	v_add_u32_e32 v57, 1, v53
	v_fma_f32 v59, -v55, v52, v50
	v_fma_f32 v60, -v56, v53, v51
	v_cmp_ge_f32_e64 s[4:5], 0, v58
	v_fma_f32 v61, -v57, v53, v51
	v_cmp_lt_f32_e64 s[6:7], 0, v59
	v_cndmask_b32_e64 v52, v52, v54, s[4:5]
	v_cmp_ge_f32_e64 s[4:5], 0, v60
	v_cndmask_b32_e64 v52, v52, v55, s[6:7]
	v_mul_f32_e32 v54, 0x37800000, v52
	v_cndmask_b32_e64 v53, v53, v56, s[4:5]
	v_cmp_lt_f32_e64 s[4:5], 0, v61
	v_cndmask_b32_e64 v52, v52, v54, s[0:1]
	v_cmp_class_f32_e64 s[0:1], v50, v21
	v_cndmask_b32_e64 v53, v53, v57, s[4:5]
	v_mul_f32_e32 v55, 0x37800000, v53
	v_cndmask_b32_e32 v53, v53, v55, vcc
	v_cmp_class_f32_e32 vcc, v51, v21
	v_cndmask_b32_e64 v50, v52, v50, s[0:1]
	v_div_scale_f32 v52, s[0:1], v50, v50, 1.0
	v_cndmask_b32_e32 v51, v53, v51, vcc
	v_div_scale_f32 v54, s[0:1], v51, v51, 1.0
	v_rcp_f32_e32 v56, v52
	v_rcp_f32_e32 v57, v54
	v_div_scale_f32 v53, vcc, 1.0, v50, 1.0
	v_fma_f32 v58, -v52, v56, 1.0
	v_fma_f32 v59, -v54, v57, 1.0
	v_fmac_f32_e32 v56, v58, v56
	v_div_scale_f32 v55, s[0:1], 1.0, v51, 1.0
	v_fmac_f32_e32 v57, v59, v57
	v_mul_f32_e32 v58, v53, v56
	v_mul_f32_e32 v59, v55, v57
	v_fma_f32 v60, -v52, v58, v53
	v_fma_f32 v61, -v54, v59, v55
	v_fmac_f32_e32 v58, v60, v56
	v_fmac_f32_e32 v59, v61, v57
	v_fma_f32 v52, -v52, v58, v53
	v_fma_f32 v53, -v54, v59, v55
	v_div_fmas_f32 v52, v52, v56, v58
	s_mov_b64 vcc, s[0:1]
	v_div_fixup_f32 v50, v52, v50, 1.0
	v_div_fmas_f32 v52, v53, v57, v59
	v_div_fixup_f32 v51, v52, v51, 1.0
	v_mul_f32_e32 v22, v50, v22
	v_mul_f32_e32 v23, v50, v23
	v_mul_f32_e32 v24, v50, v24
	v_mul_f32_e32 v25, v50, v25
	v_mul_f32_e32 v30, v50, v30
	v_mul_f32_e32 v31, v50, v31
	v_mul_f32_e32 v32, v50, v32
	v_mul_f32_e32 v33, v50, v33
	v_mul_f32_e32 v38, v50, v38
	v_mul_f32_e32 v39, v50, v39
	v_mul_f32_e32 v40, v50, v40
	v_mul_f32_e32 v41, v50, v41
	v_mul_f32_e32 v46, v50, v46
	v_mul_f32_e32 v47, v50, v47
	v_mul_f32_e32 v48, v50, v48
	v_mul_f32_e32 v49, v50, v49
	v_bfe_u32 v50, v22, 16, 1
	v_bfe_u32 v52, v23, 16, 1
	v_bfe_u32 v53, v24, 16, 1
	v_mul_f32_e32 v26, v51, v26
	v_mul_f32_e32 v28, v51, v28
	v_bfe_u32 v54, v25, 16, 1
	v_mul_f32_e32 v27, v51, v27
	v_mul_f32_e32 v29, v51, v29
	v_bfe_u32 v55, v30, 16, 1
	v_bfe_u32 v56, v31, 16, 1
	v_bfe_u32 v57, v32, 16, 1
	v_bfe_u32 v58, v33, 16, 1
	v_mul_f32_e32 v34, v51, v34
	v_mul_f32_e32 v36, v51, v36
	v_bfe_u32 v59, v38, 16, 1
	v_bfe_u32 v60, v39, 16, 1
	v_bfe_u32 v61, v40, 16, 1
	v_bfe_u32 v62, v41, 16, 1
	v_mul_f32_e32 v42, v51, v42
	v_mul_f32_e32 v44, v51, v44
	v_bfe_u32 v63, v46, 16, 1
	v_bfe_u32 v64, v47, 16, 1
	v_bfe_u32 v65, v48, 16, 1
	v_mul_f32_e32 v10, v51, v10
	v_mul_f32_e32 v11, v51, v11
	v_mul_f32_e32 v12, v51, v12
	v_add3_u32 v22, v22, v50, s29
	v_add3_u32 v23, v23, v52, s29
	v_add3_u32 v24, v24, v53, s29
	v_bfe_u32 v50, v26, 16, 1
	v_bfe_u32 v52, v28, 16, 1
	v_mul_f32_e32 v35, v51, v35
	v_mul_f32_e32 v37, v51, v37
	v_mul_f32_e32 v43, v51, v43
	v_mul_f32_e32 v45, v51, v45
	v_bfe_u32 v66, v49, 16, 1
	v_mul_f32_e32 v13, v51, v13
	v_add3_u32 v25, v25, v54, s29
	v_bfe_u32 v51, v27, 16, 1
	v_bfe_u32 v53, v29, 16, 1
	v_add3_u32 v30, v30, v55, s29
	v_add3_u32 v31, v31, v56, s29
	v_add3_u32 v32, v32, v57, s29
	v_add3_u32 v33, v33, v58, s29
	v_bfe_u32 v54, v34, 16, 1
	v_bfe_u32 v56, v36, 16, 1
	v_add3_u32 v38, v38, v59, s29
	v_add3_u32 v39, v39, v60, s29
	v_add3_u32 v40, v40, v61, s29
	v_add3_u32 v41, v41, v62, s29
	v_bfe_u32 v58, v42, 16, 1
	v_bfe_u32 v60, v44, 16, 1
	v_add3_u32 v46, v46, v63, s29
	v_add3_u32 v47, v47, v64, s29
	v_add3_u32 v48, v48, v65, s29
	v_bfe_u32 v62, v10, 16, 1
	v_bfe_u32 v63, v11, 16, 1
	v_bfe_u32 v64, v12, 16, 1
	v_lshrrev_b32_e32 v22, 16, v22
	v_lshrrev_b32_e32 v24, 16, v24
	v_add3_u32 v26, v26, v50, s29
	v_add3_u32 v28, v28, v52, s29
	v_bfe_u32 v55, v35, 16, 1
	v_bfe_u32 v57, v37, 16, 1
	v_bfe_u32 v59, v43, 16, 1
	v_bfe_u32 v61, v45, 16, 1
	v_add3_u32 v49, v49, v66, s29
	v_bfe_u32 v65, v13, 16, 1
	v_add3_u32 v27, v27, v51, s29
	v_add3_u32 v29, v29, v53, s29
	v_lshrrev_b32_e32 v30, 16, v30
	v_lshrrev_b32_e32 v32, 16, v32
	v_add3_u32 v34, v34, v54, s29
	v_add3_u32 v36, v36, v56, s29
	v_lshrrev_b32_e32 v38, 16, v38
	v_lshrrev_b32_e32 v40, 16, v40
	v_add3_u32 v42, v42, v58, s29
	v_add3_u32 v44, v44, v60, s29
	v_lshrrev_b32_e32 v46, 16, v46
	v_lshrrev_b32_e32 v48, 16, v48
	v_add3_u32 v50, v10, v62, s29
	v_add3_u32 v51, v11, v63, s29
	v_add3_u32 v52, v12, v64, s29
	v_and_or_b32 v10, v23, s15, v22
	v_and_or_b32 v11, v25, s15, v24
	v_lshrrev_b32_e32 v26, 16, v26
	v_lshrrev_b32_e32 v28, 16, v28
	v_add3_u32 v35, v35, v55, s29
	v_add3_u32 v37, v37, v57, s29
	v_add3_u32 v43, v43, v59, s29
	v_add3_u32 v45, v45, v61, s29
	v_add3_u32 v53, v13, v65, s29
	v_and_or_b32 v12, v31, s15, v30
	v_and_or_b32 v13, v33, s15, v32
	v_lshrrev_b32_e32 v30, 16, v34
	v_lshrrev_b32_e32 v31, 16, v36
	v_and_or_b32 v22, v39, s15, v38
	v_and_or_b32 v23, v41, s15, v40
	v_lshrrev_b32_e32 v32, 16, v42
	v_lshrrev_b32_e32 v33, 16, v44
	v_and_or_b32 v24, v47, s15, v46
	v_and_or_b32 v25, v49, s15, v48
	v_lshrrev_b32_e32 v34, 16, v50
	v_lshrrev_b32_e32 v36, 16, v52
	global_store_dwordx2 v[8:9], v[10:11], off offset:-1024
	v_and_or_b32 v10, v27, s15, v26
	v_and_or_b32 v11, v29, s15, v28
	global_store_dwordx2 v[8:9], v[12:13], off offset:-512
	v_and_or_b32 v12, v35, s15, v30
	v_and_or_b32 v13, v37, s15, v31
	global_store_dwordx2 v[8:9], v[22:23], off
	v_and_or_b32 v22, v43, s15, v32
	v_and_or_b32 v23, v45, s15, v33
	global_store_dwordx2 v[8:9], v[24:25], off offset:512
	v_and_or_b32 v8, v51, s15, v34
	v_and_or_b32 v9, v53, s15, v36
	global_store_dwordx2 v[6:7], v[10:11], off offset:-1024
	global_store_dwordx2 v[6:7], v[12:13], off offset:-512
	global_store_dwordx2 v[6:7], v[22:23], off
	global_store_dwordx2 v[6:7], v[8:9], off offset:512
	s_cbranch_scc0 .LBB0_42

.LBB0_204:
	s_and_b64 vcc, exec, s[4:5]
	s_cbranch_vccz .LBB0_212
	v_readlane_b32 s6, v249, 15
	v_readlane_b32 s7, v249, 16
	s_mov_b64 s[4:5], 0
	s_andn2_b64 vcc, exec, s[6:7]
	s_cbranch_vccnz .LBB0_212
	v_readlane_b32 s36, v250, 1
	v_readlane_b32 s46, v250, 11
	v_readlane_b32 s42, v250, 7
	v_readlane_b32 s46, v248, 2
	v_readlane_b32 s43, v250, 8
	s_add_u32 s6, s42, s4
	s_mul_i32 s18, s46, 0xc00
	s_addc_u32 s7, s43, s5
	s_lshl_b64 s[4:5], s[18:19], 2
	v_lshlrev_b32_e32 v0, 3, v158
	s_add_u32 s4, s6, s4
	v_and_b32_e32 v28, 0x3f8, v0
	s_addc_u32 s5, s7, s5
	v_lshlrev_b32_e32 v2, 2, v28
	v_lshl_add_u64 v[0:1], s[4:5], 0, v[2:3]
	s_mov_b64 s[6:7], 0x1000
	v_lshl_add_u64 v[16:17], v[0:1], 0, s[6:7]
	s_mov_b64 s[6:7], 0x2000
	global_load_dwordx4 v[4:7], v2, s[4:5] offset:16 nt
	global_load_dwordx4 v[8:11], v2, s[4:5] nt
	s_movk_i32 s4, 0x2000
	v_lshl_add_u64 v[24:25], v[0:1], 0, s[6:7]
	v_add_co_u32_e32 v0, vcc, s4, v0
	v_lshlrev_b32_e32 v2, 1, v28
	s_nop 0
	v_addc_co_u32_e32 v1, vcc, 0, v1, vcc
	global_load_dwordx4 v[12:15], v[0:1], off offset:-4096 nt
	s_nop 0
	global_load_dwordx4 v[16:19], v[16:17], off offset:16 nt
	s_nop 0
	global_load_dwordx4 v[20:23], v[0:1], off nt
	s_nop 0
	global_load_dwordx4 v[24:27], v[24:25], off offset:16 nt
	v_ashrrev_i32_e32 v0, 2, v158
	v_lshl_add_u64 v[28:29], s[16:17], 0, v[2:3]
	s_mov_b64 s[4:5], 0xb600000
	v_and_b32_e32 v66, 0xffffffe0, v0
	v_lshl_add_u64 v[0:1], v[28:29], 0, s[4:5]
	s_mov_b64 s[4:5], 0x7600000
	v_lshl_add_u64 v[32:33], v[28:29], 0, s[4:5]
	s_mov_b64 s[4:5], 0x13600000
	v_lshl_add_u64 v[34:35], v[28:29], 0, s[4:5]
	v_readlane_b32 s4, v249, 29
	s_mov_b32 s6, s2
	v_readlane_b32 s37, v250, 2
	v_add_u32_e32 v67, s4, v66
	v_readlane_b32 s38, v250, 3
	v_readlane_b32 s39, v250, 4
	v_readlane_b32 s40, v250, 5
	v_readlane_b32 s41, v250, 6
	v_readlane_b32 s44, v250, 9
	v_readlane_b32 s45, v250, 10
	v_readlane_b32 s47, v250, 12
	v_readlane_b32 s48, v250, 13
	v_readlane_b32 s49, v250, 14
	v_readlane_b32 s50, v250, 15
	v_readlane_b32 s51, v250, 16
	s_waitcnt vmcnt(4)
	v_mov_b32_e32 v36, v8
	v_mov_b32_e32 v37, v10
	v_mov_b32_e32 v10, v9
	v_mov_b32_e32 v8, v4
	v_mov_b32_e32 v9, v6
	v_mov_b32_e32 v6, v5
	s_waitcnt vmcnt(3)
	v_mov_b32_e32 v4, v12
	v_mov_b32_e32 v5, v14
	s_waitcnt vmcnt(1)
	v_mov_b32_e32 v38, v20
	v_mov_b32_e32 v39, v22
	v_mov_b32_e32 v14, v13
	v_mov_b32_e32 v22, v21
	v_mov_b32_e32 v12, v16
	v_mov_b32_e32 v13, v18
	s_waitcnt vmcnt(0)
	v_mov_b32_e32 v20, v24
	v_mov_b32_e32 v21, v26
	v_mov_b32_e32 v18, v17
	v_mov_b32_e32 v26, v25
.LBB0_207:
	v_lshl_add_u32 v28, s6, 7, v66
	v_and_b32_e32 v2, 0x1fe0, v28
	v_cmp_ne_u32_e32 vcc, 0, v2
	v_mov_b32_e32 v2, v3
	s_mov_b32 s7, 0
	v_mov_b32_e32 v52, 0
	v_mov_b64_e32 v[16:17], v[2:3]
	v_mov_b64_e32 v[24:25], v[2:3]
	v_mov_b32_e32 v54, 0
	v_mov_b32_e32 v53, 0
	v_mov_b32_e32 v55, 0
	v_mov_b32_e32 v56, 0
	v_mov_b32_e32 v30, 0
	v_mov_b32_e32 v57, 0
	v_mov_b32_e32 v31, 0
	v_mov_b32_e32 v40, 0
	v_mov_b32_e32 v41, 0
	v_mov_b32_e32 v42, 0
	v_mov_b32_e32 v43, 0
	s_and_saveexec_b64 s[4:5], vcc
	s_cbranch_execz .LBB0_209
	v_ashrrev_i32_e32 v29, 31, v28
	v_lshlrev_b64 v[16:17], 11, v[28:29]
	v_lshl_add_u64 v[16:17], v[0:1], 0, v[16:17]
	global_load_dwordx4 v[28:31], v[16:17], off offset:-4096 nt
	global_load_dwordx4 v[44:47], v[16:17], off offset:-2048 nt
	s_waitcnt vmcnt(1)
	v_lshlrev_b32_e32 v42, 16, v28
	v_and_b32_e32 v40, 0xffff0000, v28
	v_lshlrev_b32_e32 v43, 16, v29
	v_and_b32_e32 v41, 0xffff0000, v29
	v_lshlrev_b32_e32 v24, 16, v30
	v_and_b32_e32 v16, 0xffff0000, v30
	v_lshlrev_b32_e32 v25, 16, v31
	v_and_b32_e32 v17, 0xffff0000, v31
	s_waitcnt vmcnt(0)
	v_lshlrev_b32_e32 v52, 16, v44
	v_and_b32_e32 v54, 0xffff0000, v44
	v_lshlrev_b32_e32 v53, 16, v45
	v_and_b32_e32 v55, 0xffff0000, v45
	v_lshlrev_b32_e32 v56, 16, v46
	v_and_b32_e32 v30, 0xffff0000, v46
	v_lshlrev_b32_e32 v57, 16, v47
	v_and_b32_e32 v31, 0xffff0000, v47

.LBB0_210:
	v_add_u32_e32 v28, s7, v67
	v_ashrrev_i32_e32 v29, 31, v28
	v_lshlrev_b64 v[68:69], 11, v[28:29]
	v_lshl_add_u64 v[44:45], v[32:33], 0, v[68:69]
	v_lshl_add_u64 v[48:49], v[0:1], 0, v[68:69]
	global_load_dwordx4 v[44:47], v[44:45], off nt
	s_add_i32 s7, s7, 4
	global_load_dwordx4 v[48:51], v[48:49], off nt
	s_cmp_eq_u32 s7, 32
	s_waitcnt vmcnt(1)
	v_lshlrev_b32_e32 v63, 16, v45
	v_lshlrev_b32_e32 v62, 16, v44
	s_waitcnt vmcnt(0)
	v_lshlrev_b32_e32 v61, 16, v49
	v_lshlrev_b32_e32 v60, 16, v48
	v_and_b32_e32 v59, 0xffff0000, v49
	v_and_b32_e32 v58, 0xffff0000, v48
	v_pk_mul_f32 v[48:49], v[4:5], v[52:53]
	v_and_b32_e32 v45, 0xffff0000, v45
	v_pk_fma_f32 v[42:43], v[36:37], v[42:43], v[48:49]
	v_pk_mul_f32 v[48:49], v[14:15], v[54:55]
	v_and_b32_e32 v44, 0xffff0000, v44
	v_pk_fma_f32 v[40:41], v[10:11], v[40:41], v[48:49]
	v_pk_mul_f32 v[48:49], v[12:13], v[56:57]
	v_pk_fma_f32 v[40:41], v[22:23], v[58:59], v[40:41]
	v_lshlrev_b32_e32 v65, 16, v51
	v_lshlrev_b32_e32 v64, 16, v50
	v_pk_fma_f32 v[24:25], v[8:9], v[24:25], v[48:49]
	v_pk_mul_f32 v[40:41], v[40:41], v[44:45]
	v_lshlrev_b32_e32 v45, 16, v47
	v_lshlrev_b32_e32 v44, 16, v46
	v_pk_fma_f32 v[24:25], v[20:21], v[64:65], v[24:25]
	v_pk_fma_f32 v[42:43], v[38:39], v[60:61], v[42:43]
	v_pk_mul_f32 v[24:25], v[24:25], v[44:45]
	v_pk_mul_f32 v[44:45], v[18:19], v[30:31]
	v_pk_mul_f32 v[42:43], v[42:43], v[62:63]
	v_and_b32_e32 v63, 0xffff0000, v51
	v_and_b32_e32 v62, 0xffff0000, v50
	v_pk_fma_f32 v[16:17], v[6:7], v[16:17], v[44:45]
	v_and_b32_e32 v47, 0xffff0000, v47
	v_and_b32_e32 v46, 0xffff0000, v46
	v_pk_fma_f32 v[16:17], v[26:27], v[62:63], v[16:17]
	v_bfe_u32 v44, v41, 16, 1
	v_pk_mul_f32 v[16:17], v[16:17], v[46:47]
	v_bfe_u32 v45, v40, 16, 1
	v_bfe_u32 v2, v17, 16, 1
	v_bfe_u32 v29, v16, 16, 1
	v_add3_u32 v40, v40, v45, s3
	v_add3_u32 v41, v41, v44, s3
	v_add3_u32 v16, v16, v29, s3
	v_add3_u32 v2, v17, v2, s3
	v_bfe_u32 v17, v42, 16, 1
	v_bfe_u32 v29, v43, 16, 1
	v_bfe_u32 v44, v24, 16, 1
	v_bfe_u32 v45, v25, 16, 1
	v_add3_u32 v25, v25, v45, s3
	v_add3_u32 v24, v24, v44, s3
	v_add3_u32 v29, v43, v29, s3
	v_add3_u32 v17, v42, v17, s3
	v_lshrrev_b32_e32 v17, 16, v17
	v_lshrrev_b32_e32 v29, 16, v29
	v_lshrrev_b32_e32 v24, 16, v24
	v_lshrrev_b32_e32 v25, 16, v25
	v_and_or_b32 v43, v2, s33, v25
	v_and_or_b32 v42, v16, s33, v24
	v_and_or_b32 v41, v41, s33, v29
	v_and_or_b32 v40, v40, s33, v17
	v_lshl_add_u64 v[16:17], v[34:35], 0, v[68:69]
	global_store_dwordx4 v[16:17], v[40:43], off
	v_add_u32_e32 v16, 1, v28
	v_ashrrev_i32_e32 v17, 31, v16
	v_lshlrev_b64 v[16:17], 11, v[16:17]
	v_lshl_add_u64 v[24:25], v[32:33], 0, v[16:17]
	global_load_dwordx4 v[40:43], v[24:25], off nt
	v_lshl_add_u64 v[24:25], v[0:1], 0, v[16:17]
	global_load_dwordx4 v[44:47], v[24:25], off nt
	v_pk_mul_f32 v[48:49], v[4:5], v[60:61]
	v_lshl_add_u64 v[16:17], v[34:35], 0, v[16:17]
	v_pk_fma_f32 v[48:49], v[36:37], v[52:53], v[48:49]
	s_waitcnt vmcnt(1)
	v_lshlrev_b32_e32 v25, 16, v41
	v_lshlrev_b32_e32 v24, 16, v40
	s_waitcnt vmcnt(0)
	v_lshlrev_b32_e32 v51, 16, v45
	v_lshlrev_b32_e32 v50, 16, v44
	v_pk_fma_f32 v[48:49], v[38:39], v[50:51], v[48:49]
	v_and_b32_e32 v45, 0xffff0000, v45
	v_pk_mul_f32 v[24:25], v[48:49], v[24:25]
	v_pk_mul_f32 v[48:49], v[14:15], v[58:59]
	v_and_b32_e32 v44, 0xffff0000, v44
	v_pk_fma_f32 v[48:49], v[10:11], v[54:55], v[48:49]
	v_and_b32_e32 v41, 0xffff0000, v41
	v_and_b32_e32 v40, 0xffff0000, v40
	v_pk_fma_f32 v[48:49], v[22:23], v[44:45], v[48:49]
	v_pk_mul_f32 v[54:55], v[12:13], v[64:65]
	v_pk_mul_f32 v[40:41], v[48:49], v[40:41]
	v_lshlrev_b32_e32 v49, 16, v47
	v_lshlrev_b32_e32 v48, 16, v46
	v_pk_fma_f32 v[54:55], v[8:9], v[56:57], v[54:55]
	v_lshlrev_b32_e32 v53, 16, v43
	v_lshlrev_b32_e32 v52, 16, v42
	v_pk_fma_f32 v[54:55], v[20:21], v[48:49], v[54:55]
	v_and_b32_e32 v47, 0xffff0000, v47
	v_pk_mul_f32 v[52:53], v[54:55], v[52:53]
	v_pk_mul_f32 v[54:55], v[18:19], v[62:63]
	v_and_b32_e32 v46, 0xffff0000, v46
	v_pk_fma_f32 v[30:31], v[6:7], v[30:31], v[54:55]
	v_and_b32_e32 v43, 0xffff0000, v43
	v_and_b32_e32 v42, 0xffff0000, v42
	v_pk_fma_f32 v[30:31], v[26:27], v[46:47], v[30:31]
	s_nop 0
	v_pk_mul_f32 v[30:31], v[30:31], v[42:43]
	v_bfe_u32 v42, v41, 16, 1
	v_bfe_u32 v2, v31, 16, 1
	v_bfe_u32 v29, v30, 16, 1
	v_bfe_u32 v43, v40, 16, 1
	v_add3_u32 v40, v40, v43, s3
	v_add3_u32 v41, v41, v42, s3
	v_add3_u32 v29, v30, v29, s3
	v_add3_u32 v2, v31, v2, s3
	v_bfe_u32 v30, v24, 16, 1
	v_bfe_u32 v31, v25, 16, 1
	v_bfe_u32 v42, v52, 16, 1
	v_bfe_u32 v43, v53, 16, 1
	v_add3_u32 v43, v53, v43, s3
	v_add3_u32 v42, v52, v42, s3
	v_add3_u32 v25, v25, v31, s3
	v_add3_u32 v24, v24, v30, s3
	v_lshrrev_b32_e32 v24, 16, v24
	v_lshrrev_b32_e32 v25, 16, v25
	v_lshrrev_b32_e32 v30, 16, v42
	v_lshrrev_b32_e32 v31, 16, v43
	v_and_or_b32 v43, v2, s33, v31
	v_and_or_b32 v42, v29, s33, v30
	v_and_or_b32 v41, v41, s33, v25
	v_and_or_b32 v40, v40, s33, v24
	global_store_dwordx4 v[16:17], v[40:43], off
	v_add_u32_e32 v16, 2, v28
	v_ashrrev_i32_e32 v17, 31, v16
	v_lshlrev_b64 v[30:31], 11, v[16:17]
	v_lshl_add_u64 v[16:17], v[32:33], 0, v[30:31]
	global_load_dwordx4 v[52:55], v[16:17], off nt
	v_lshl_add_u64 v[16:17], v[0:1], 0, v[30:31]
	global_load_dwordx4 v[68:71], v[16:17], off nt
	v_add_u32_e32 v28, 3, v28
	v_lshl_add_u64 v[30:31], v[34:35], 0, v[30:31]
	s_waitcnt vmcnt(1)
	v_lshlrev_b32_e32 v17, 16, v53
	v_lshlrev_b32_e32 v16, 16, v52
	v_and_b32_e32 v25, 0xffff0000, v53
	v_and_b32_e32 v24, 0xffff0000, v52
	v_pk_mul_f32 v[52:53], v[4:5], v[50:51]
	s_waitcnt vmcnt(0)
	v_lshlrev_b32_e32 v43, 16, v69
	v_lshlrev_b32_e32 v42, 16, v68
	v_pk_fma_f32 v[52:53], v[36:37], v[60:61], v[52:53]
	v_and_b32_e32 v41, 0xffff0000, v69
	v_pk_fma_f32 v[52:53], v[38:39], v[42:43], v[52:53]
	v_and_b32_e32 v40, 0xffff0000, v68
	v_pk_mul_f32 v[52:53], v[52:53], v[16:17]
	v_pk_mul_f32 v[16:17], v[14:15], v[44:45]
	v_pk_mul_f32 v[60:61], v[12:13], v[48:49]
	v_pk_fma_f32 v[16:17], v[10:11], v[58:59], v[16:17]
	v_pk_fma_f32 v[60:61], v[8:9], v[64:65], v[60:61]
	v_pk_fma_f32 v[16:17], v[22:23], v[40:41], v[16:17]
	v_lshlrev_b32_e32 v59, 16, v55
	v_pk_mul_f32 v[56:57], v[16:17], v[24:25]
	v_lshlrev_b32_e32 v25, 16, v71
	v_lshlrev_b32_e32 v24, 16, v70
	v_lshlrev_b32_e32 v58, 16, v54
	v_pk_fma_f32 v[60:61], v[20:21], v[24:25], v[60:61]
	v_and_b32_e32 v17, 0xffff0000, v71
	v_pk_mul_f32 v[58:59], v[60:61], v[58:59]
	v_pk_mul_f32 v[60:61], v[18:19], v[46:47]
	v_and_b32_e32 v16, 0xffff0000, v70
	v_pk_fma_f32 v[60:61], v[6:7], v[62:63], v[60:61]
	v_and_b32_e32 v55, 0xffff0000, v55
	v_and_b32_e32 v54, 0xffff0000, v54
	v_pk_fma_f32 v[60:61], v[26:27], v[16:17], v[60:61]
	s_nop 0
	v_pk_mul_f32 v[54:55], v[60:61], v[54:55]
	v_bfe_u32 v60, v57, 16, 1
	v_bfe_u32 v2, v55, 16, 1
	v_bfe_u32 v29, v54, 16, 1
	v_bfe_u32 v61, v56, 16, 1
	v_add3_u32 v57, v57, v60, s3
	v_bfe_u32 v60, v58, 16, 1
	v_add3_u32 v56, v56, v61, s3
	v_add3_u32 v29, v54, v29, s3
	v_add3_u32 v2, v55, v2, s3
	v_bfe_u32 v54, v52, 16, 1
	v_bfe_u32 v55, v53, 16, 1
	v_bfe_u32 v61, v59, 16, 1
	v_add3_u32 v58, v58, v60, s3
	v_add3_u32 v59, v59, v61, s3
	v_add3_u32 v53, v53, v55, s3
	v_add3_u32 v52, v52, v54, s3
	v_lshrrev_b32_e32 v54, 16, v58
	v_lshrrev_b32_e32 v52, 16, v52
	v_lshrrev_b32_e32 v53, 16, v53
	v_lshrrev_b32_e32 v55, 16, v59
	v_and_or_b32 v54, v29, s33, v54
	v_ashrrev_i32_e32 v29, 31, v28
	v_and_or_b32 v55, v2, s33, v55
	v_and_or_b32 v53, v57, s33, v53
	v_and_or_b32 v52, v56, s33, v52
	v_lshlrev_b64 v[58:59], 11, v[28:29]
	global_store_dwordx4 v[30:31], v[52:55], off
	v_lshl_add_u64 v[28:29], v[32:33], 0, v[58:59]
	global_load_dwordx4 v[28:31], v[28:29], off nt
	v_lshl_add_u64 v[52:53], v[0:1], 0, v[58:59]
	global_load_dwordx4 v[60:63], v[52:53], off nt
	s_waitcnt vmcnt(1)
	v_lshlrev_b32_e32 v57, 16, v29
	v_lshlrev_b32_e32 v56, 16, v28
	s_waitcnt vmcnt(0)
	v_lshlrev_b32_e32 v53, 16, v61
	v_lshlrev_b32_e32 v52, 16, v60
	v_and_b32_e32 v55, 0xffff0000, v61
	v_and_b32_e32 v54, 0xffff0000, v60
	v_pk_mul_f32 v[60:61], v[4:5], v[42:43]
	v_and_b32_e32 v29, 0xffff0000, v29
	v_pk_fma_f32 v[50:51], v[36:37], v[50:51], v[60:61]
	v_and_b32_e32 v28, 0xffff0000, v28
	v_pk_fma_f32 v[50:51], v[38:39], v[52:53], v[50:51]
	v_and_b32_e32 v61, 0xffff0000, v31
	v_pk_mul_f32 v[50:51], v[50:51], v[56:57]
	v_pk_mul_f32 v[56:57], v[14:15], v[40:41]
	v_and_b32_e32 v60, 0xffff0000, v30
	v_pk_fma_f32 v[44:45], v[10:11], v[44:45], v[56:57]
	v_lshlrev_b32_e32 v57, 16, v63
	v_pk_fma_f32 v[44:45], v[22:23], v[54:55], v[44:45]
	v_lshlrev_b32_e32 v56, 16, v62
	v_pk_mul_f32 v[28:29], v[44:45], v[28:29]
	v_lshlrev_b32_e32 v45, 16, v31
	v_lshlrev_b32_e32 v44, 16, v30
	v_and_b32_e32 v31, 0xffff0000, v63
	v_and_b32_e32 v30, 0xffff0000, v62
	v_pk_mul_f32 v[62:63], v[12:13], v[24:25]
	s_nop 0
	v_pk_fma_f32 v[48:49], v[8:9], v[48:49], v[62:63]
	s_nop 0
	v_pk_fma_f32 v[48:49], v[20:21], v[56:57], v[48:49]
	s_nop 0
	v_pk_mul_f32 v[44:45], v[48:49], v[44:45]
	v_pk_mul_f32 v[48:49], v[18:19], v[16:17]
	s_nop 0
	v_pk_fma_f32 v[46:47], v[6:7], v[46:47], v[48:49]
	v_bfe_u32 v49, v29, 16, 1
	v_pk_fma_f32 v[46:47], v[26:27], v[30:31], v[46:47]
	v_add3_u32 v29, v29, v49, s3
	v_pk_mul_f32 v[46:47], v[46:47], v[60:61]
	v_bfe_u32 v60, v28, 16, 1
	v_bfe_u32 v2, v47, 16, 1
	v_bfe_u32 v48, v46, 16, 1
	v_add3_u32 v28, v28, v60, s3
	v_add3_u32 v46, v46, v48, s3
	v_add3_u32 v2, v47, v2, s3
	v_bfe_u32 v47, v50, 16, 1
	v_bfe_u32 v48, v51, 16, 1
	v_bfe_u32 v49, v44, 16, 1
	v_bfe_u32 v60, v45, 16, 1
	v_add3_u32 v45, v45, v60, s3
	v_add3_u32 v44, v44, v49, s3
	v_add3_u32 v48, v51, v48, s3
	v_add3_u32 v47, v50, v47, s3
	v_lshrrev_b32_e32 v49, 16, v47
	v_lshrrev_b32_e32 v48, 16, v48
	v_lshrrev_b32_e32 v44, 16, v44
	v_lshrrev_b32_e32 v45, 16, v45
	v_and_or_b32 v47, v2, s33, v45
	v_and_or_b32 v46, v46, s33, v44
	v_and_or_b32 v45, v29, s33, v48
	v_and_or_b32 v44, v28, s33, v49
	v_lshl_add_u64 v[28:29], v[34:35], 0, v[58:59]
	global_store_dwordx4 v[28:29], v[44:47], off
	s_cbranch_scc0 .LBB0_210
	s_add_i32 s6, s6, s86
	s_cmpk_gt_i32 s6, 0xff
	v_add_u32_e32 v67, s28, v67
	s_cbranch_scc0 .LBB0_207

.LBB0_217:
	s_cmp_ge_i32 s10, s12
	s_mov_b64 s[4:5], -1
	s_cbranch_scc0 .LBB0_247
	s_sub_i32 s8, s10, s12
	s_cmp_ge_i32 s8, s11
	s_cbranch_scc0 .LBB0_232
	s_sub_i32 s6, s8, s11
	s_cmpk_gt_i32 s6, 0x1ff
	s_cbranch_scc0 .LBB0_229
	s_cmpk_gt_u32 s6, 0xcff
	s_cbranch_scc0 .LBB0_222
	s_lshl_b32 s4, s6, 1
	s_and_b32 s4, s4, 0x7fffffc0
	s_lshl_b32 s5, s10, 5
	s_addk_i32 s4, 0xe600
	s_and_b32 s7, s5, 0x3e0
	v_or_b32_e32 v2, s4, v0
	s_lshl_b32 s18, s7, 2
	v_lshl_add_u64 v[32:33], v[46:47], 0, s[18:19]
	v_lshlrev_b64 v[4:5], 12, v[2:3]
	v_or_b32_e32 v8, 8, v2
	v_mov_b32_e32 v9, v3
	v_lshl_add_u64 v[4:5], v[32:33], 0, v[4:5]
	v_lshlrev_b64 v[8:9], 12, v[8:9]
	global_load_dwordx4 v[4:7], v[4:5], off nt
	v_lshl_add_u64 v[8:9], v[32:33], 0, v[8:9]
	v_or_b32_e32 v12, 16, v2
	v_mov_b32_e32 v13, v3
	global_load_dwordx4 v[8:11], v[8:9], off nt
	v_lshlrev_b64 v[12:13], 12, v[12:13]
	v_lshl_add_u64 v[12:13], v[32:33], 0, v[12:13]
	v_or_b32_e32 v16, 24, v2
	v_mov_b32_e32 v17, v3
	global_load_dwordx4 v[12:15], v[12:13], off nt
	v_lshlrev_b64 v[16:17], 12, v[16:17]
	v_lshl_add_u64 v[16:17], v[32:33], 0, v[16:17]
	v_or_b32_e32 v20, 32, v2
	v_mov_b32_e32 v21, v3
	global_load_dwordx4 v[16:19], v[16:17], off nt
	v_lshlrev_b64 v[20:21], 12, v[20:21]
	v_lshl_add_u64 v[20:21], v[32:33], 0, v[20:21]
	v_or_b32_e32 v24, 40, v2
	v_mov_b32_e32 v25, v3
	global_load_dwordx4 v[20:23], v[20:21], off nt
	v_lshlrev_b64 v[24:25], 12, v[24:25]
	v_lshl_add_u64 v[24:25], v[32:33], 0, v[24:25]
	v_or_b32_e32 v28, 48, v2
	v_mov_b32_e32 v29, v3
	global_load_dwordx4 v[24:27], v[24:25], off nt
	v_lshlrev_b64 v[28:29], 12, v[28:29]
	v_lshl_add_u64 v[28:29], v[32:33], 0, v[28:29]
	v_or_b32_e32 v2, 56, v2
	global_load_dwordx4 v[28:31], v[28:29], off nt
	v_lshlrev_b64 v[34:35], 12, v[2:3]
	v_lshl_add_u64 v[32:33], v[32:33], 0, v[34:35]
	global_load_dwordx4 v[32:35], v[32:33], off nt
	v_add_u32_e32 v2, v60, v61
	s_mov_b32 s5, s19
	s_waitcnt vmcnt(7)
	ds_write2_b32 v2, v4, v5 offset1:1
	ds_write2_b32 v2, v6, v7 offset0:2 offset1:3
	v_add_u32_e32 v4, 0x420, v2
	s_waitcnt vmcnt(6)
	ds_write2_b32 v4, v8, v9 offset1:1
	v_add_u32_e32 v4, 0x428, v2
	ds_write2_b32 v4, v10, v11 offset1:1
	v_add_u32_e32 v4, 0x840, v2
	s_waitcnt vmcnt(5)
	ds_write2_b32 v4, v12, v13 offset1:1
	v_add_u32_e32 v4, 0x848, v2
	ds_write2_b32 v4, v14, v15 offset1:1
	v_add_u32_e32 v4, 0xc60, v2
	s_waitcnt vmcnt(4)
	ds_write2_b32 v4, v16, v17 offset1:1
	v_add_u32_e32 v4, 0xc68, v2
	ds_write2_b32 v4, v18, v19 offset1:1
	v_add_u32_e32 v4, 0x1080, v2
	s_waitcnt vmcnt(3)
	ds_write2_b32 v4, v20, v21 offset1:1
	v_add_u32_e32 v4, 0x1088, v2
	ds_write2_b32 v4, v22, v23 offset1:1
	v_add_u32_e32 v4, 0x14a0, v2
	s_waitcnt vmcnt(2)
	ds_write2_b32 v4, v24, v25 offset1:1
	v_add_u32_e32 v4, 0x14a8, v2
	ds_write2_b32 v4, v26, v27 offset1:1
	v_add_u32_e32 v4, 0x18c0, v2
	s_waitcnt vmcnt(1)
	ds_write2_b32 v4, v28, v29 offset1:1
	v_add_u32_e32 v4, 0x18c8, v2
	ds_write2_b32 v4, v30, v31 offset1:1
	v_add_u32_e32 v4, 0x1ce0, v2
	v_add_u32_e32 v2, 0x1ce8, v2
	s_waitcnt vmcnt(0)
	ds_write2_b32 v4, v32, v33 offset1:1
	ds_write2_b32 v2, v34, v35 offset1:1
	s_waitcnt lgkmcnt(0)
	ds_read2_b32 v[10:11], v65 offset0:33 offset1:41
	ds_read2_b32 v[12:13], v65 offset1:8
	ds_read2_b32 v[14:15], v65 offset0:66 offset1:74
	ds_read2_b32 v[16:17], v65 offset0:99 offset1:107
	ds_read2_b32 v[18:19], v65 offset0:132 offset1:140
	ds_read2_b32 v[20:21], v65 offset0:165 offset1:173
	ds_read2_b32 v[22:23], v65 offset0:198 offset1:206
	ds_read2_b32 v[24:25], v65 offset0:231 offset1:239
	s_waitcnt lgkmcnt(7)
	v_bfe_u32 v6, v10, 16, 1
	s_waitcnt lgkmcnt(6)
	v_bfe_u32 v2, v12, 16, 1
	v_add3_u32 v2, v12, v2, s3
	v_lshrrev_b32_e32 v2, 16, v2
	v_add3_u32 v6, v10, v6, s3
	v_and_or_b32 v6, v6, s33, v2
	s_waitcnt lgkmcnt(5)
	v_bfe_u32 v2, v14, 16, 1
	v_add3_u32 v2, v14, v2, s3
	s_waitcnt lgkmcnt(4)
	v_bfe_u32 v7, v16, 16, 1
	v_lshrrev_b32_e32 v2, 16, v2
	v_add3_u32 v7, v16, v7, s3
	v_and_or_b32 v7, v7, s33, v2
	s_waitcnt lgkmcnt(3)
	v_bfe_u32 v2, v18, 16, 1
	v_add3_u32 v2, v18, v2, s3
	s_waitcnt lgkmcnt(2)
	v_bfe_u32 v8, v20, 16, 1
	v_lshrrev_b32_e32 v2, 16, v2
	v_add3_u32 v8, v20, v8, s3
	v_and_or_b32 v8, v8, s33, v2
	s_waitcnt lgkmcnt(1)
	v_bfe_u32 v2, v22, 16, 1
	v_add3_u32 v2, v22, v2, s3
	s_waitcnt lgkmcnt(0)
	v_bfe_u32 v9, v24, 16, 1
	v_lshrrev_b32_e32 v2, 16, v2
	v_add3_u32 v9, v24, v9, s3
	v_and_or_b32 v9, v9, s33, v2
	v_or_b32_e32 v2, s7, v0
	v_mul_u32_u24_e32 v2, 0xb00, v2
	v_lshl_add_u64 v[4:5], s[4:5], 1, v[38:39]
	v_lshlrev_b32_e32 v2, 1, v2
	v_lshl_add_u64 v[26:27], v[4:5], 0, v[2:3]
	v_bfe_u32 v2, v13, 16, 1
	global_store_dwordx4 v[26:27], v[6:9], off
	v_add3_u32 v2, v13, v2, s3
	v_lshrrev_b32_e32 v2, 16, v2
	v_bfe_u32 v6, v11, 16, 1
	v_add3_u32 v6, v11, v6, s3
	v_and_or_b32 v6, v6, s33, v2
	v_bfe_u32 v2, v15, 16, 1
	v_add3_u32 v2, v15, v2, s3
	v_bfe_u32 v7, v17, 16, 1
	v_lshrrev_b32_e32 v2, 16, v2
	v_add3_u32 v7, v17, v7, s3
	v_and_or_b32 v7, v7, s33, v2
	v_bfe_u32 v2, v19, 16, 1
	v_add3_u32 v2, v19, v2, s3
	v_bfe_u32 v8, v21, 16, 1
	v_lshrrev_b32_e32 v2, 16, v2
	v_add3_u32 v8, v21, v8, s3
	v_and_or_b32 v8, v8, s33, v2
	v_bfe_u32 v2, v23, 16, 1
	v_add3_u32 v2, v23, v2, s3
	v_bfe_u32 v9, v25, 16, 1
	v_lshrrev_b32_e32 v2, 16, v2
	v_add3_u32 v9, v25, v9, s3
	v_and_or_b32 v9, v9, s33, v2
	v_or_b32_e32 v2, s7, v62
	v_mul_u32_u24_e32 v2, 0xb00, v2
	v_lshlrev_b32_e32 v2, 1, v2
	v_lshl_add_u64 v[10:11], v[4:5], 0, v[2:3]
	global_store_dwordx4 v[10:11], v[6:9], off
	ds_read2_b32 v[10:11], v65 offset0:16 offset1:24
	ds_read2_b32 v[12:13], v65 offset0:49 offset1:57
	ds_read2_b32 v[14:15], v65 offset0:82 offset1:90
	ds_read2_b32 v[16:17], v65 offset0:115 offset1:123
	ds_read2_b32 v[18:19], v65 offset0:148 offset1:156
	ds_read2_b32 v[20:21], v65 offset0:181 offset1:189
	ds_read2_b32 v[22:23], v65 offset0:214 offset1:222
	ds_read2_b32 v[24:25], v65 offset0:247 offset1:255
	s_waitcnt lgkmcnt(7)
	v_bfe_u32 v2, v10, 16, 1
	v_add3_u32 v2, v10, v2, s3
	s_waitcnt lgkmcnt(6)
	v_bfe_u32 v6, v12, 16, 1
	v_lshrrev_b32_e32 v2, 16, v2
	v_add3_u32 v6, v12, v6, s3
	v_and_or_b32 v6, v6, s33, v2
	s_waitcnt lgkmcnt(5)
	v_bfe_u32 v2, v14, 16, 1
	v_add3_u32 v2, v14, v2, s3
	s_waitcnt lgkmcnt(4)
	v_bfe_u32 v7, v16, 16, 1
	v_lshrrev_b32_e32 v2, 16, v2
	v_add3_u32 v7, v16, v7, s3
	v_and_or_b32 v7, v7, s33, v2
	s_waitcnt lgkmcnt(3)
	v_bfe_u32 v2, v18, 16, 1
	v_add3_u32 v2, v18, v2, s3
	s_waitcnt lgkmcnt(2)
	v_bfe_u32 v8, v20, 16, 1
	v_lshrrev_b32_e32 v2, 16, v2
	v_add3_u32 v8, v20, v8, s3
	v_and_or_b32 v8, v8, s33, v2
	s_waitcnt lgkmcnt(1)
	v_bfe_u32 v2, v22, 16, 1
	v_add3_u32 v2, v22, v2, s3
	s_waitcnt lgkmcnt(0)
	v_bfe_u32 v9, v24, 16, 1
	v_lshrrev_b32_e32 v2, 16, v2
	v_add3_u32 v9, v24, v9, s3
	v_and_or_b32 v9, v9, s33, v2
	v_or_b32_e32 v2, s7, v63
	v_mul_u32_u24_e32 v2, 0xb00, v2
	v_lshlrev_b32_e32 v2, 1, v2
	v_lshl_add_u64 v[26:27], v[4:5], 0, v[2:3]
	v_bfe_u32 v2, v11, 16, 1
	global_store_dwordx4 v[26:27], v[6:9], off
	v_add3_u32 v2, v11, v2, s3
	v_lshrrev_b32_e32 v2, 16, v2
	v_bfe_u32 v6, v13, 16, 1
	v_add3_u32 v6, v13, v6, s3
	v_and_or_b32 v6, v6, s33, v2
	v_bfe_u32 v2, v15, 16, 1
	v_add3_u32 v2, v15, v2, s3
	v_bfe_u32 v7, v17, 16, 1
	v_lshrrev_b32_e32 v2, 16, v2
	v_add3_u32 v7, v17, v7, s3
	v_and_or_b32 v7, v7, s33, v2
	v_bfe_u32 v2, v19, 16, 1
	v_add3_u32 v2, v19, v2, s3
	v_bfe_u32 v8, v21, 16, 1
	v_lshrrev_b32_e32 v2, 16, v2
	v_add3_u32 v8, v21, v8, s3
	v_and_or_b32 v8, v8, s33, v2
	v_bfe_u32 v2, v23, 16, 1
	v_add3_u32 v2, v23, v2, s3
	v_bfe_u32 v9, v25, 16, 1
	v_lshrrev_b32_e32 v2, 16, v2
	v_add3_u32 v9, v25, v9, s3
	v_and_or_b32 v9, v9, s33, v2
	v_or_b32_e32 v2, s7, v64
	v_mul_u32_u24_e32 v2, 0xb00, v2
	v_lshlrev_b32_e32 v2, 1, v2
	v_lshl_add_u64 v[4:5], v[4:5], 0, v[2:3]
	global_store_dwordx4 v[4:5], v[6:9], off
	s_waitcnt lgkmcnt(0)
	s_mov_b64 s[4:5], 0
.LBB0_222:
	s_andn2_b64 vcc, exec, s[4:5]
	s_cbranch_vccnz .LBB0_228
	s_add_i32 s4, s6, 0xfe00
	s_and_b32 s5, s4, 0xffff
	s_mul_i32 s5, s5, 0xba2f
	s_lshr_b32 s5, s5, 23
	s_mul_i32 s7, s5, 0xb0
	s_sub_i32 s4, s4, s7
	s_lshl_b32 s7, s5, 6
	s_and_b32 s4, s4, 0xffff
	v_or_b32_e32 v24, s7, v0
	s_lshl_b32 s18, s4, 7
	v_mul_u32_u24_e32 v2, 0x1600, v24
	v_lshl_add_u64 v[4:5], v[48:49], 0, s[18:19]
	s_movk_i32 s5, 0x5800
	v_lshlrev_b32_e32 v2, 2, v2
	v_mad_u64_u32 v[6:7], s[16:17], v24, s5, v[4:5]
	v_lshl_add_u64 v[20:21], v[4:5], 0, v[2:3]
	s_mov_b32 s5, 0x2c000
	v_add_co_u32_e32 v8, vcc, s5, v20
	s_mov_b32 s5, 0x58000
	s_nop 0
	v_addc_co_u32_e32 v9, vcc, 0, v21, vcc
	v_add_co_u32_e32 v12, vcc, s5, v20
	s_mov_b32 s5, 0x84000
	s_nop 0
	v_addc_co_u32_e32 v13, vcc, 0, v21, vcc
	v_add_co_u32_e32 v14, vcc, s5, v20
	s_mov_b32 s5, 0xb0000
	s_nop 0
	v_addc_co_u32_e32 v15, vcc, 0, v21, vcc
	v_lshlrev_b32_e32 v2, 2, v24
	v_or_b32_e32 v24, s7, v62
	global_load_dwordx4 v[4:7], v[6:7], off nt
	s_nop 0
	global_load_dwordx4 v[8:11], v[8:9], off nt
	s_nop 0
	global_load_dwordx4 v[16:19], v[12:13], off nt
	s_nop 0
	global_load_dwordx4 v[12:15], v[14:15], off nt
	v_add_co_u32_e32 v22, vcc, s5, v20
	global_load_dword v2, v2, s[30:31]
	v_lshlrev_b32_e32 v24, 2, v24
	v_addc_co_u32_e32 v23, vcc, 0, v21, vcc
	s_mov_b32 s5, 0xdc000
	global_load_dword v34, v24, s[30:31]
	v_add_co_u32_e32 v26, vcc, s5, v20
	v_or_b32_e32 v24, s7, v63
	v_or_b32_e32 v30, s7, v64
	v_or_b32_e32 v35, s7, v68
	v_addc_co_u32_e32 v27, vcc, 0, v21, vcc
	v_lshlrev_b32_e32 v24, 2, v24
	v_lshlrev_b32_e32 v30, 2, v30
	v_lshlrev_b32_e32 v35, 2, v35
	global_load_dword v72, v24, s[30:31]
	s_nop 0
	global_load_dwordx4 v[22:25], v[22:23], off nt
	s_nop 0
	global_load_dwordx4 v[26:29], v[26:27], off nt
	s_mov_b32 s5, 0x108000
	global_load_dword v74, v30, s[30:31]
	global_load_dword v78, v35, s[30:31]
	v_or_b32_e32 v30, s7, v66
	v_lshlrev_b32_e32 v30, 2, v30
	global_load_dword v76, v30, s[30:31]
	v_or_b32_e32 v35, s7, v69
	v_lshlrev_b32_e32 v35, 2, v35
	global_load_dword v80, v35, s[30:31]
	v_add_co_u32_e32 v30, vcc, s5, v20
	s_mov_b32 s5, 0x134000
	s_nop 0
	v_addc_co_u32_e32 v31, vcc, 0, v21, vcc
	global_load_dwordx4 v[30:33], v[30:31], off nt
	v_or_b32_e32 v35, s7, v70
	v_add_co_u32_e32 v20, vcc, s5, v20
	v_lshlrev_b32_e32 v35, 2, v35
	s_nop 0
	v_addc_co_u32_e32 v21, vcc, 0, v21, vcc
	global_load_dword v82, v35, s[30:31]
	global_load_dwordx4 v[56:59], v[20:21], off nt
	v_add_u32_e32 v20, v60, v61
	v_add_u32_e32 v21, 0x420, v20
	s_lshl_b32 s9, s4, 5
	s_lshl_b32 s16, s4, 6
	s_cmpk_gt_u32 s4, 0x57
	s_mov_b64 s[4:5], -1
	s_waitcnt vmcnt(11)
	v_pk_mul_f32 v[4:5], v[4:5], v[2:3] op_sel_hi:[1,0]
	v_pk_mul_f32 v[6:7], v[6:7], v[2:3] op_sel_hi:[1,0]
	ds_write2_b32 v20, v4, v5 offset1:1
	ds_write2_b32 v20, v6, v7 offset0:2 offset1:3
	v_add_u32_e32 v2, 0x428, v20
	s_waitcnt vmcnt(10)
	v_pk_mul_f32 v[4:5], v[8:9], v[34:35] op_sel_hi:[1,0]
	v_pk_mul_f32 v[6:7], v[10:11], v[34:35] op_sel_hi:[1,0]
	ds_write2_b32 v21, v4, v5 offset1:1
	ds_write2_b32 v2, v6, v7 offset1:1
	v_add_u32_e32 v2, 0x840, v20
	s_waitcnt vmcnt(9)
	v_pk_mul_f32 v[4:5], v[16:17], v[72:73] op_sel_hi:[1,0]
	ds_write2_b32 v2, v4, v5 offset1:1
	v_pk_mul_f32 v[4:5], v[18:19], v[72:73] op_sel_hi:[1,0]
	v_add_u32_e32 v2, 0x848, v20
	ds_write2_b32 v2, v4, v5 offset1:1
	s_waitcnt vmcnt(6)
	v_pk_mul_f32 v[4:5], v[12:13], v[74:75] op_sel_hi:[1,0]
	v_add_u32_e32 v2, 0xc60, v20
	ds_write2_b32 v2, v4, v5 offset1:1
	v_pk_mul_f32 v[4:5], v[14:15], v[74:75] op_sel_hi:[1,0]
	v_add_u32_e32 v2, 0xc68, v20
	ds_write2_b32 v2, v4, v5 offset1:1
	s_waitcnt vmcnt(4)
	v_pk_mul_f32 v[4:5], v[22:23], v[76:77] op_sel_hi:[1,0]
	v_add_u32_e32 v2, v60, v67
	ds_write2_b32 v2, v4, v5 offset1:1
	v_pk_mul_f32 v[4:5], v[24:25], v[76:77] op_sel_hi:[1,0]
	ds_write2_b32 v2, v4, v5 offset0:2 offset1:3
	v_pk_mul_f32 v[4:5], v[26:27], v[78:79] op_sel_hi:[1,0]
	v_add_u32_e32 v6, 0x420, v2
	ds_write2_b32 v6, v4, v5 offset1:1
	v_pk_mul_f32 v[4:5], v[28:29], v[78:79] op_sel_hi:[1,0]
	v_add_u32_e32 v6, 0x428, v2
	ds_write2_b32 v6, v4, v5 offset1:1
	s_waitcnt vmcnt(2)
	v_pk_mul_f32 v[4:5], v[30:31], v[80:81] op_sel_hi:[1,0]
	v_add_u32_e32 v6, 0x840, v2
	ds_write2_b32 v6, v4, v5 offset1:1
	v_pk_mul_f32 v[4:5], v[32:33], v[80:81] op_sel_hi:[1,0]
	v_add_u32_e32 v6, 0x848, v2
	ds_write2_b32 v6, v4, v5 offset1:1
	s_waitcnt vmcnt(0)
	v_pk_mul_f32 v[4:5], v[56:57], v[82:83] op_sel_hi:[1,0]
	v_add_u32_e32 v6, 0xc60, v2
	ds_write2_b32 v6, v4, v5 offset1:1
	v_pk_mul_f32 v[4:5], v[58:59], v[82:83] op_sel_hi:[1,0]
	v_add_u32_e32 v2, 0xc68, v2
	ds_write2_b32 v2, v4, v5 offset1:1
	s_waitcnt lgkmcnt(0)
	s_cbranch_scc0 .LBB0_225
	s_add_i32 s4, s16, 0x7fffea00
	s_and_b32 s4, s4, 0x7fffff00
	s_and_b32 s5, s9, 0x60
	s_or_b32 s4, s5, s4
	s_or_b32 s15, s4, 0x80
	s_mov_b64 s[4:5], 0

.LBB0_229:
	s_andn2_b64 vcc, exec, s[4:5]
	s_cbranch_vccnz .LBB0_231
	s_ashr_i32 s4, s6, 31
	s_lshr_b32 s4, s4, 27
	s_add_i32 s4, s6, s4
	s_and_b32 s5, s4, 0x7ffffe0
	s_lshl_b32 s4, s4, 1
	s_sub_i32 s5, s6, s5
	s_and_b32 s6, s4, 0xffffffc0
	s_lshl_b32 s4, s5, 5
	v_or_b32_e32 v32, s6, v0
	s_ashr_i32 s5, s4, 31
	v_ashrrev_i32_e32 v33, 31, v32
	v_or_b32_e32 v8, 8, v32
	v_lshl_add_u64 v[34:35], s[4:5], 2, v[50:51]
	v_lshlrev_b64 v[4:5], 12, v[32:33]
	v_ashrrev_i32_e32 v9, 31, v8
	v_lshl_add_u64 v[4:5], v[34:35], 0, v[4:5]
	v_lshlrev_b64 v[8:9], 12, v[8:9]
	v_or_b32_e32 v12, 16, v32
	global_load_dwordx4 v[4:7], v[4:5], off nt
	v_lshl_add_u64 v[8:9], v[34:35], 0, v[8:9]
	v_ashrrev_i32_e32 v13, 31, v12
	global_load_dwordx4 v[8:11], v[8:9], off nt
	v_lshlrev_b64 v[12:13], 12, v[12:13]
	v_or_b32_e32 v16, 24, v32
	v_lshl_add_u64 v[12:13], v[34:35], 0, v[12:13]
	v_ashrrev_i32_e32 v17, 31, v16
	global_load_dwordx4 v[12:15], v[12:13], off nt
	v_lshlrev_b64 v[16:17], 12, v[16:17]
	v_or_b32_e32 v20, 32, v32
	v_lshl_add_u64 v[16:17], v[34:35], 0, v[16:17]
	v_ashrrev_i32_e32 v21, 31, v20
	global_load_dwordx4 v[16:19], v[16:17], off nt
	v_lshlrev_b64 v[20:21], 12, v[20:21]
	v_or_b32_e32 v24, 40, v32
	v_lshl_add_u64 v[20:21], v[34:35], 0, v[20:21]
	v_ashrrev_i32_e32 v25, 31, v24
	global_load_dwordx4 v[20:23], v[20:21], off nt
	v_lshlrev_b64 v[24:25], 12, v[24:25]
	v_or_b32_e32 v28, 48, v32
	v_lshl_add_u64 v[24:25], v[34:35], 0, v[24:25]
	v_ashrrev_i32_e32 v29, 31, v28
	global_load_dwordx4 v[24:27], v[24:25], off nt
	v_lshlrev_b64 v[28:29], 12, v[28:29]
	v_or_b32_e32 v32, 56, v32
	v_lshl_add_u64 v[28:29], v[34:35], 0, v[28:29]
	v_ashrrev_i32_e32 v33, 31, v32
	global_load_dwordx4 v[28:31], v[28:29], off nt
	v_lshlrev_b64 v[32:33], 12, v[32:33]
	v_lshl_add_u64 v[32:33], v[34:35], 0, v[32:33]
	global_load_dwordx4 v[32:35], v[32:33], off nt
	v_add_u32_e32 v2, v60, v61
	s_ashr_i32 s7, s6, 31
	s_waitcnt vmcnt(7)
	ds_write2_b32 v2, v4, v5 offset1:1
	ds_write2_b32 v2, v6, v7 offset0:2 offset1:3
	v_add_u32_e32 v4, 0x420, v2
	s_waitcnt vmcnt(6)
	ds_write2_b32 v4, v8, v9 offset1:1
	v_add_u32_e32 v4, 0x428, v2
	ds_write2_b32 v4, v10, v11 offset1:1
	v_add_u32_e32 v4, 0x840, v2
	s_waitcnt vmcnt(5)
	ds_write2_b32 v4, v12, v13 offset1:1
	v_add_u32_e32 v4, 0x848, v2
	ds_write2_b32 v4, v14, v15 offset1:1
	v_add_u32_e32 v4, 0xc60, v2
	s_waitcnt vmcnt(4)
	ds_write2_b32 v4, v16, v17 offset1:1
	v_add_u32_e32 v4, 0xc68, v2
	ds_write2_b32 v4, v18, v19 offset1:1
	v_add_u32_e32 v4, 0x1080, v2
	s_waitcnt vmcnt(3)
	ds_write2_b32 v4, v20, v21 offset1:1
	v_add_u32_e32 v4, 0x1088, v2
	ds_write2_b32 v4, v22, v23 offset1:1
	v_add_u32_e32 v4, 0x14a0, v2
	s_waitcnt vmcnt(2)
	ds_write2_b32 v4, v24, v25 offset1:1
	v_add_u32_e32 v4, 0x14a8, v2
	ds_write2_b32 v4, v26, v27 offset1:1
	v_add_u32_e32 v4, 0x18c0, v2
	v_or_b32_e32 v26, s4, v0
	s_waitcnt vmcnt(1)
	ds_write2_b32 v4, v28, v29 offset1:1
	v_add_u32_e32 v4, 0x18c8, v2
	ds_write2_b32 v4, v30, v31 offset1:1
	v_add_u32_e32 v4, 0x1ce0, v2
	v_add_u32_e32 v2, 0x1ce8, v2
	s_waitcnt vmcnt(0)
	ds_write2_b32 v4, v32, v33 offset1:1
	ds_write2_b32 v2, v34, v35 offset1:1
	s_waitcnt lgkmcnt(0)
	ds_read2_b32 v[10:11], v65 offset0:33 offset1:41
	ds_read2_b32 v[12:13], v65 offset1:8
	ds_read2_b32 v[14:15], v65 offset0:66 offset1:74
	ds_read2_b32 v[16:17], v65 offset0:99 offset1:107
	ds_read2_b32 v[18:19], v65 offset0:132 offset1:140
	ds_read2_b32 v[20:21], v65 offset0:165 offset1:173
	ds_read2_b32 v[22:23], v65 offset0:198 offset1:206
	ds_read2_b32 v[24:25], v65 offset0:231 offset1:239
	s_waitcnt lgkmcnt(7)
	v_bfe_u32 v6, v10, 16, 1
	s_waitcnt lgkmcnt(6)
	v_bfe_u32 v2, v12, 16, 1
	v_add3_u32 v2, v12, v2, s3
	v_lshrrev_b32_e32 v2, 16, v2
	v_add3_u32 v6, v10, v6, s3
	v_and_or_b32 v6, v6, s33, v2
	s_waitcnt lgkmcnt(5)
	v_bfe_u32 v2, v14, 16, 1
	v_add3_u32 v2, v14, v2, s3
	s_waitcnt lgkmcnt(4)
	v_bfe_u32 v7, v16, 16, 1
	v_lshrrev_b32_e32 v2, 16, v2
	v_add3_u32 v7, v16, v7, s3
	v_and_or_b32 v7, v7, s33, v2
	s_waitcnt lgkmcnt(3)
	v_bfe_u32 v2, v18, 16, 1
	v_add3_u32 v2, v18, v2, s3
	s_waitcnt lgkmcnt(2)
	v_bfe_u32 v8, v20, 16, 1
	v_lshrrev_b32_e32 v2, 16, v2
	v_add3_u32 v8, v20, v8, s3
	v_and_or_b32 v8, v8, s33, v2
	s_waitcnt lgkmcnt(1)
	v_bfe_u32 v2, v22, 16, 1
	v_add3_u32 v2, v22, v2, s3
	s_waitcnt lgkmcnt(0)
	v_bfe_u32 v9, v24, 16, 1
	v_ashrrev_i32_e32 v27, 31, v26
	v_lshl_add_u64 v[4:5], s[6:7], 1, v[42:43]
	v_lshrrev_b32_e32 v2, 16, v2
	v_add3_u32 v9, v24, v9, s3
	v_lshlrev_b64 v[26:27], 11, v[26:27]
	v_and_or_b32 v9, v9, s33, v2
	v_lshl_add_u64 v[26:27], v[4:5], 0, v[26:27]
	v_bfe_u32 v2, v13, 16, 1
	global_store_dwordx4 v[26:27], v[6:9], off
	v_add3_u32 v2, v13, v2, s3
	v_lshrrev_b32_e32 v2, 16, v2
	v_bfe_u32 v6, v11, 16, 1
	v_add3_u32 v6, v11, v6, s3
	v_and_or_b32 v6, v6, s33, v2
	v_bfe_u32 v2, v15, 16, 1
	v_add3_u32 v2, v15, v2, s3
	v_bfe_u32 v7, v17, 16, 1
	v_lshrrev_b32_e32 v2, 16, v2
	v_add3_u32 v7, v17, v7, s3
	v_and_or_b32 v7, v7, s33, v2
	v_bfe_u32 v2, v19, 16, 1
	v_add3_u32 v2, v19, v2, s3
	v_bfe_u32 v8, v21, 16, 1
	v_lshrrev_b32_e32 v2, 16, v2
	v_add3_u32 v8, v21, v8, s3
	v_and_or_b32 v8, v8, s33, v2
	v_bfe_u32 v2, v23, 16, 1
	v_or_b32_e32 v10, s4, v62
	v_add3_u32 v2, v23, v2, s3
	v_bfe_u32 v9, v25, 16, 1
	v_ashrrev_i32_e32 v11, 31, v10
	v_lshrrev_b32_e32 v2, 16, v2
	v_add3_u32 v9, v25, v9, s3
	v_lshlrev_b64 v[10:11], 11, v[10:11]
	v_and_or_b32 v9, v9, s33, v2
	v_lshl_add_u64 v[10:11], v[4:5], 0, v[10:11]
	global_store_dwordx4 v[10:11], v[6:9], off
	ds_read2_b32 v[10:11], v65 offset0:49 offset1:57
	ds_read2_b32 v[12:13], v65 offset0:16 offset1:24
	ds_read2_b32 v[14:15], v65 offset0:82 offset1:90
	ds_read2_b32 v[16:17], v65 offset0:115 offset1:123
	ds_read2_b32 v[18:19], v65 offset0:148 offset1:156
	ds_read2_b32 v[20:21], v65 offset0:181 offset1:189
	ds_read2_b32 v[22:23], v65 offset0:214 offset1:222
	ds_read2_b32 v[24:25], v65 offset0:247 offset1:255
	s_waitcnt lgkmcnt(7)
	v_bfe_u32 v6, v10, 16, 1
	s_waitcnt lgkmcnt(6)
	v_bfe_u32 v2, v12, 16, 1
	v_add3_u32 v2, v12, v2, s3
	v_lshrrev_b32_e32 v2, 16, v2
	v_add3_u32 v6, v10, v6, s3
	v_and_or_b32 v6, v6, s33, v2
	s_waitcnt lgkmcnt(5)
	v_bfe_u32 v2, v14, 16, 1
	v_add3_u32 v2, v14, v2, s3
	s_waitcnt lgkmcnt(4)
	v_bfe_u32 v7, v16, 16, 1
	v_lshrrev_b32_e32 v2, 16, v2
	v_add3_u32 v7, v16, v7, s3
	v_and_or_b32 v7, v7, s33, v2
	s_waitcnt lgkmcnt(3)
	v_bfe_u32 v2, v18, 16, 1
	v_add3_u32 v2, v18, v2, s3
	s_waitcnt lgkmcnt(2)
	v_bfe_u32 v8, v20, 16, 1
	v_lshrrev_b32_e32 v2, 16, v2
	v_add3_u32 v8, v20, v8, s3
	v_and_or_b32 v8, v8, s33, v2
	s_waitcnt lgkmcnt(1)
	v_bfe_u32 v2, v22, 16, 1
	v_or_b32_e32 v26, s4, v63
	v_add3_u32 v2, v22, v2, s3
	s_waitcnt lgkmcnt(0)
	v_bfe_u32 v9, v24, 16, 1
	v_ashrrev_i32_e32 v27, 31, v26
	v_lshrrev_b32_e32 v2, 16, v2
	v_add3_u32 v9, v24, v9, s3
	v_lshlrev_b64 v[26:27], 11, v[26:27]
	v_and_or_b32 v9, v9, s33, v2
	v_lshl_add_u64 v[26:27], v[4:5], 0, v[26:27]
	v_bfe_u32 v2, v13, 16, 1
	global_store_dwordx4 v[26:27], v[6:9], off
	v_add3_u32 v2, v13, v2, s3
	v_lshrrev_b32_e32 v2, 16, v2
	v_bfe_u32 v6, v11, 16, 1
	v_add3_u32 v6, v11, v6, s3
	v_and_or_b32 v6, v6, s33, v2
	v_bfe_u32 v2, v15, 16, 1
	v_add3_u32 v2, v15, v2, s3
	v_bfe_u32 v7, v17, 16, 1
	v_lshrrev_b32_e32 v2, 16, v2
	v_add3_u32 v7, v17, v7, s3
	v_and_or_b32 v7, v7, s33, v2
	v_bfe_u32 v2, v19, 16, 1
	v_add3_u32 v2, v19, v2, s3
	v_bfe_u32 v8, v21, 16, 1
	v_lshrrev_b32_e32 v2, 16, v2
	v_add3_u32 v8, v21, v8, s3
	v_and_or_b32 v8, v8, s33, v2
	v_bfe_u32 v2, v23, 16, 1
	v_or_b32_e32 v10, s4, v64
	v_add3_u32 v2, v23, v2, s3
	v_bfe_u32 v9, v25, 16, 1
	v_ashrrev_i32_e32 v11, 31, v10
	v_lshrrev_b32_e32 v2, 16, v2
	v_add3_u32 v9, v25, v9, s3
	v_lshlrev_b64 v[10:11], 11, v[10:11]
	v_and_or_b32 v9, v9, s33, v2
	v_lshl_add_u64 v[4:5], v[4:5], 0, v[10:11]
	global_store_dwordx4 v[4:5], v[6:9], off
	s_waitcnt lgkmcnt(0)

.LBB0_232:
	s_andn2_b64 vcc, exec, s[4:5]
	s_cbranch_vccnz .LBB0_246
	s_ashr_i32 s4, s8, 31
	s_lshr_b32 s4, s4, 27
	s_add_i32 s4, s8, s4
	s_and_b32 s5, s4, 0x7ffffe0
	s_lshl_b32 s4, s4, 1
	s_andn2_b32 s4, s4, 63
	s_sub_i32 s5, s8, s5
	v_or_b32_e32 v56, s4, v0
	s_lshl_b32 s6, s5, 5
	v_or_b32_e32 v8, 8, v56
	s_ashr_i32 s7, s6, 31
	v_ashrrev_i32_e32 v57, 31, v56
	v_ashrrev_i32_e32 v9, 31, v8
	v_lshl_add_u64 v[4:5], s[6:7], 2, v[52:53]
	v_lshlrev_b64 v[6:7], 12, v[56:57]
	v_lshlrev_b64 v[8:9], 12, v[8:9]
	v_lshl_add_u64 v[6:7], v[4:5], 0, v[6:7]
	v_lshl_add_u64 v[8:9], v[4:5], 0, v[8:9]
	global_load_dwordx4 v[32:35], v[6:7], off nt
	global_load_dwordx4 v[28:31], v[8:9], off nt
	v_or_b32_e32 v6, 16, v56
	v_or_b32_e32 v8, 24, v56
	v_ashrrev_i32_e32 v7, 31, v6
	v_ashrrev_i32_e32 v9, 31, v8
	v_lshlrev_b64 v[6:7], 12, v[6:7]
	v_lshlrev_b64 v[8:9], 12, v[8:9]
	v_lshl_add_u64 v[6:7], v[4:5], 0, v[6:7]
	v_lshl_add_u64 v[8:9], v[4:5], 0, v[8:9]
	global_load_dwordx4 v[24:27], v[6:7], off nt
	global_load_dwordx4 v[20:23], v[8:9], off nt
	v_or_b32_e32 v6, 32, v56
	v_or_b32_e32 v8, 40, v56
	v_ashrrev_i32_e32 v7, 31, v6
	v_ashrrev_i32_e32 v9, 31, v8
	v_lshlrev_b64 v[6:7], 12, v[6:7]
	v_lshlrev_b64 v[8:9], 12, v[8:9]
	v_lshl_add_u64 v[6:7], v[4:5], 0, v[6:7]
	v_lshl_add_u64 v[8:9], v[4:5], 0, v[8:9]
	global_load_dwordx4 v[16:19], v[6:7], off nt
	global_load_dwordx4 v[12:15], v[8:9], off nt
	v_or_b32_e32 v6, 48, v56
	v_or_b32_e32 v8, 56, v56
	v_ashrrev_i32_e32 v7, 31, v6
	v_ashrrev_i32_e32 v9, 31, v8
	v_lshlrev_b64 v[6:7], 12, v[6:7]
	v_lshlrev_b64 v[8:9], 12, v[8:9]
	v_lshl_add_u64 v[6:7], v[4:5], 0, v[6:7]
	v_lshl_add_u64 v[4:5], v[4:5], 0, v[8:9]
	global_load_dwordx4 v[8:11], v[6:7], off nt
	s_nop 0
	global_load_dwordx4 v[4:7], v[4:5], off nt
	v_cndmask_b32_e64 v2, 0, 1, s[20:21]
	v_cmp_ne_u32_e64 s[36:37], 1, v2
	s_andn2_b64 vcc, exec, s[20:21]
	s_cbranch_vccnz .LBB0_255
	v_lshl_add_u64 v[56:57], v[56:57], 2, s[40:41]
	s_ashr_i32 s5, s4, 31
	global_load_dword v2, v[56:57], off
	v_lshl_add_u64 v[56:57], s[4:5], 0, v[0:1]
	v_lshl_add_u64 v[56:57], v[56:57], 2, s[40:41]
	global_load_dword v71, v[56:57], off offset:32
	s_waitcnt vmcnt(1)
	v_mul_f32_e32 v2, 0x3e38aa3b, v2
	v_pk_mul_f32 v[56:57], v[32:33], v[2:3] op_sel_hi:[1,0]
	v_pk_mul_f32 v[58:59], v[34:35], v[2:3] op_sel_hi:[1,0]
	s_waitcnt vmcnt(0)
	v_mul_f32_e32 v2, 0x3e38aa3b, v71
	s_cbranch_execnz .LBB0_236

.LBB0_247:
	s_andn2_b64 vcc, exec, s[4:5]
	s_cbranch_vccnz .LBB0_216
	s_mov_b64 s[4:5], -1
	s_and_b64 vcc, exec, s[38:39]
	s_cbranch_vccz .LBB0_264
	s_ashr_i32 s4, s10, 31
	s_lshr_b32 s4, s4, 26
	s_add_i32 s4, s10, s4
	s_and_b32 s6, s4, 0xffffffc0
	s_sub_i32 s4, s10, s6
	v_or_b32_e32 v56, s6, v0
	s_lshl_b32 s4, s4, 5
	v_or_b32_e32 v8, 8, v56
	s_ashr_i32 s5, s4, 31
	v_ashrrev_i32_e32 v57, 31, v56
	v_ashrrev_i32_e32 v9, 31, v8
	v_lshl_add_u64 v[4:5], s[4:5], 2, v[44:45]
	v_lshlrev_b64 v[6:7], 13, v[56:57]
	v_lshlrev_b64 v[8:9], 13, v[8:9]
	v_lshl_add_u64 v[6:7], v[4:5], 0, v[6:7]
	v_lshl_add_u64 v[8:9], v[4:5], 0, v[8:9]
	global_load_dwordx4 v[32:35], v[6:7], off nt
	global_load_dwordx4 v[28:31], v[8:9], off nt
	v_or_b32_e32 v6, 16, v56
	v_or_b32_e32 v8, 24, v56
	v_ashrrev_i32_e32 v7, 31, v6
	v_ashrrev_i32_e32 v9, 31, v8
	v_lshlrev_b64 v[6:7], 13, v[6:7]
	v_lshlrev_b64 v[8:9], 13, v[8:9]
	v_lshl_add_u64 v[6:7], v[4:5], 0, v[6:7]
	v_lshl_add_u64 v[8:9], v[4:5], 0, v[8:9]
	global_load_dwordx4 v[24:27], v[6:7], off nt
	global_load_dwordx4 v[20:23], v[8:9], off nt
	v_or_b32_e32 v6, 32, v56
	v_or_b32_e32 v8, 40, v56
	v_ashrrev_i32_e32 v7, 31, v6
	v_ashrrev_i32_e32 v9, 31, v8
	v_lshlrev_b64 v[6:7], 13, v[6:7]
	v_lshlrev_b64 v[8:9], 13, v[8:9]
	v_lshl_add_u64 v[6:7], v[4:5], 0, v[6:7]
	v_lshl_add_u64 v[8:9], v[4:5], 0, v[8:9]
	global_load_dwordx4 v[16:19], v[6:7], off nt
	global_load_dwordx4 v[12:15], v[8:9], off nt
	v_or_b32_e32 v6, 48, v56
	v_or_b32_e32 v8, 56, v56
	v_ashrrev_i32_e32 v7, 31, v6
	v_ashrrev_i32_e32 v9, 31, v8
	v_lshlrev_b64 v[6:7], 13, v[6:7]
	v_lshlrev_b64 v[8:9], 13, v[8:9]
	v_lshl_add_u64 v[6:7], v[4:5], 0, v[6:7]
	v_lshl_add_u64 v[4:5], v[4:5], 0, v[8:9]
	global_load_dwordx4 v[8:11], v[6:7], off nt
	s_nop 0
	global_load_dwordx4 v[4:7], v[4:5], off nt
	v_cndmask_b32_e64 v58, 0, 1, s[24:25]
	v_mov_b32_e32 v2, 1.0
	v_cmp_ne_u32_e64 s[36:37], 1, v58
	s_andn2_b64 vcc, exec, s[24:25]
	v_mov_b32_e32 v58, 1.0
	s_cbranch_vccnz .LBB0_251
	v_readlane_b32 s48, v250, 1
	v_readlane_b32 s58, v250, 11
	v_readlane_b32 s59, v250, 12
	s_ashr_i32 s7, s6, 31
	v_readlane_b32 s49, v250, 2
	v_lshl_add_u64 v[56:57], v[56:57], 2, s[58:59]
	global_load_dword v56, v[56:57], off
	v_readlane_b32 s50, v250, 3
	v_readlane_b32 s51, v250, 4
	v_readlane_b32 s52, v250, 5
	v_readlane_b32 s53, v250, 6
	v_readlane_b32 s54, v250, 7
	v_readlane_b32 s55, v250, 8
	v_readlane_b32 s56, v250, 9
	v_readlane_b32 s57, v250, 10
	v_readlane_b32 s60, v250, 13
	v_readlane_b32 s61, v250, 14
	v_readlane_b32 s62, v250, 15
	v_readlane_b32 s63, v250, 16
	s_waitcnt vmcnt(0)
	v_pk_mul_f32 v[32:33], v[32:33], v[56:57] op_sel_hi:[1,0]
	v_pk_mul_f32 v[34:35], v[34:35], v[56:57] op_sel_hi:[1,0]
	v_lshl_add_u64 v[56:57], s[6:7], 0, v[0:1]
	v_lshl_add_u64 v[56:57], v[56:57], 2, s[58:59]
	global_load_dword v58, v[56:57], off offset:32

.LBB0_264:
	s_and_b64 vcc, exec, s[4:5]
	s_cbranch_vccz .LBB0_216
	s_mul_hi_i32 s4, s10, 0x2aaaaaab
	s_lshr_b32 s5, s4, 31
	s_ashr_i32 s4, s4, 4
	s_add_i32 s4, s4, s5
	s_mul_i32 s5, s4, 0x60
	s_sub_i32 s8, s10, s5
	s_lshl_b32 s6, s4, 6
	s_lshl_b32 s4, s8, 5
	v_or_b32_e32 v56, s6, v0
	s_ashr_i32 s5, s4, 31
	v_lshl_add_u64 v[4:5], s[4:5], 2, v[54:55]
	s_movk_i32 s5, 0x3000
	v_or_b32_e32 v2, 8, v56
	v_mad_i64_i32 v[6:7], s[16:17], v56, s5, v[4:5]
	v_mad_i64_i32 v[8:9], s[16:17], v2, s5, v[4:5]
	v_or_b32_e32 v2, 16, v56
	global_load_dwordx4 v[32:35], v[6:7], off nt
	global_load_dwordx4 v[28:31], v[8:9], off nt
	v_mad_i64_i32 v[6:7], s[16:17], v2, s5, v[4:5]
	v_or_b32_e32 v2, 24, v56
	v_mad_i64_i32 v[8:9], s[16:17], v2, s5, v[4:5]
	v_or_b32_e32 v2, 32, v56
	global_load_dwordx4 v[24:27], v[6:7], off nt
	global_load_dwordx4 v[20:23], v[8:9], off nt
	v_mad_i64_i32 v[6:7], s[16:17], v2, s5, v[4:5]
	v_or_b32_e32 v2, 40, v56
	v_mad_i64_i32 v[8:9], s[16:17], v2, s5, v[4:5]
	v_or_b32_e32 v2, 48, v56
	global_load_dwordx4 v[16:19], v[6:7], off nt
	global_load_dwordx4 v[12:15], v[8:9], off nt
	v_mad_i64_i32 v[6:7], s[16:17], v2, s5, v[4:5]
	v_or_b32_e32 v2, 56, v56
	v_mad_i64_i32 v[4:5], s[16:17], v2, s5, v[4:5]
	global_load_dwordx4 v[8:11], v[6:7], off nt
	s_nop 0
	global_load_dwordx4 v[4:7], v[4:5], off nt
	v_cndmask_b32_e64 v57, 0, 1, s[20:21]
	v_mov_b32_e32 v2, 1.0
	v_cmp_ne_u32_e64 s[36:37], 1, v57
	s_andn2_b64 vcc, exec, s[20:21]
	v_mov_b32_e32 v58, 1.0
	s_cbranch_vccnz .LBB0_267
	v_ashrrev_i32_e32 v57, 31, v56
	v_lshl_add_u64 v[56:57], v[56:57], 2, s[40:41]
	global_load_dword v56, v[56:57], off
	s_ashr_i32 s7, s6, 31
	s_waitcnt vmcnt(0)
	v_pk_mul_f32 v[32:33], v[32:33], v[56:57] op_sel_hi:[1,0]
	v_pk_mul_f32 v[34:35], v[34:35], v[56:57] op_sel_hi:[1,0]
	v_lshl_add_u64 v[56:57], s[6:7], 0, v[0:1]
	v_lshl_add_u64 v[56:57], v[56:57], 2, s[40:41]
	global_load_dword v58, v[56:57], off offset:32
